# v51 + T21: the 32 bf16 dwordx2 stores of each residual-norm epilogue (P2,P8,P10) merged into 16 dwordx4 via v_permlane16_swap, vmcnt recomputed
# speedup vs baseline: 1.0126x; 1.0068x over previous
.LBB0_232:
	v_bfe_u32 v253, v220, 4, 1
	v_mul_u32_u24_e32 v253, 24, v253
	v_lshl_add_u32 v64, s54, 8, v216
	v_lshl_or_b32 v140, s55, 8, v218
	v_ashrrev_i32_e32 v65, 31, v64
	v_readlane_b32 s60, v252, 0
	v_ashrrev_i32_e32 v141, 31, v140
	s_waitcnt lgkmcnt(0)
	v_lshlrev_b64 v[0:1], 13, v[64:65]
	v_readlane_b32 s61, v252, 1
	v_lshlrev_b64 v[16:17], 2, v[140:141]
	v_readlane_b32 s74, v252, 14
	v_lshl_add_u64 v[212:213], s[60:61], 0, v[0:1]
	v_lshl_add_u64 v[0:1], v[212:213], 0, v[16:17]
	v_readlane_b32 s75, v252, 15
	global_load_dwordx4 v[28:31], v[0:1], off
	global_load_dwordx4 v[40:43], v[0:1], off offset:64
	global_load_dwordx4 v[52:55], v[0:1], off offset:512
	v_lshl_add_u64 v[2:3], s[74:75], 0, v[16:17]
	global_load_dwordx4 v[12:15], v[2:3], off
	global_load_dwordx4 v[8:11], v[2:3], off offset:64
	global_load_dwordx4 v[4:7], v[2:3], off offset:512
	global_load_dwordx4 v[60:63], v[0:1], off offset:576
	v_or_b32_e32 v66, 16, v64
	v_or_b32_e32 v214, 32, v64
	v_ashrrev_i32_e32 v67, 31, v66
	v_ashrrev_i32_e32 v215, 31, v214
	v_lshlrev_b64 v[18:19], 13, v[66:67]
	v_lshlrev_b64 v[20:21], 13, v[214:215]
	v_lshl_add_u64 v[18:19], s[60:61], 0, v[18:19]
	v_lshl_add_u64 v[20:21], s[60:61], 0, v[20:21]
	global_load_dwordx4 v[0:3], v[2:3], off offset:576
	v_lshl_add_u64 v[18:19], v[18:19], 0, v[16:17]
	v_lshl_add_u64 v[16:17], v[20:21], 0, v[16:17]
	global_load_dwordx4 v[56:59], v[18:19], off
	global_load_dwordx4 v[48:51], v[18:19], off offset:64
	global_load_dwordx4 v[36:39], v[18:19], off offset:512
	global_load_dwordx4 v[24:27], v[18:19], off offset:576
	global_load_dwordx4 v[44:47], v[16:17], off
	global_load_dwordx4 v[32:35], v[16:17], off offset:64
	global_load_dwordx4 v[20:23], v[16:17], off offset:512
	s_nop 0
	global_load_dwordx4 v[16:19], v[16:17], off offset:576
	v_and_b32_e32 v225, 64, v223
	v_xor_b32_e32 v224, 16, v223
	v_add_u32_e32 v225, 64, v225
	v_xor_b32_e32 v226, 32, v223
	v_cmp_lt_i32_e32 vcc, v224, v225
	v_readlane_b32 s62, v252, 2
	v_readlane_b32 s63, v252, 3
	v_readlane_b32 s64, v252, 4
	v_readlane_b32 s65, v252, 5
	v_readlane_b32 s66, v252, 6
	v_readlane_b32 s67, v252, 7
	v_readlane_b32 s68, v252, 8
	v_readlane_b32 s69, v252, 9
	v_readlane_b32 s70, v252, 10
	v_readlane_b32 s71, v252, 11
	v_readlane_b32 s72, v252, 12
	v_readlane_b32 s73, v252, 13
	v_cndmask_b32_e32 v224, v223, v224, vcc
	v_cmp_lt_i32_e32 vcc, v226, v225
	v_readlane_b32 s60, v252, 16
	v_readlane_b32 s74, v252, 30
	v_cndmask_b32_e32 v228, v223, v226, vcc
	v_lshlrev_b64 v[226:227], 11, v[64:65]
	v_lshl_add_u64 v[226:227], v[226:227], 0, v[140:141]
	v_readlane_b32 s75, v252, 31
	v_lshlrev_b32_e32 v225, 2, v224
	v_lshlrev_b32_e32 v224, 2, v228
	v_lshl_add_u64 v[228:229], v[226:227], 2, s[74:75]
	v_lshlrev_b64 v[226:227], 1, v[226:227]
	v_add_u32_e32 v226, v226, v253
	v_lshl_add_u64 v[230:231], s[12:13], 0, v[226:227]
	v_or_b32_e32 v232, 0, v226
	v_mov_b32_e32 v233, v227
	v_lshl_add_u64 v[232:233], s[12:13], 0, v[232:233]
	v_readlane_b32 s61, v252, 17
	v_readlane_b32 s62, v252, 18
	v_readlane_b32 s63, v252, 19
	v_readlane_b32 s64, v252, 20
	v_readlane_b32 s65, v252, 21
	v_readlane_b32 s66, v252, 22
	v_readlane_b32 s67, v252, 23
	v_readlane_b32 s68, v252, 24
	v_readlane_b32 s69, v252, 25
	v_readlane_b32 s70, v252, 26
	v_readlane_b32 s71, v252, 27
	v_readlane_b32 s72, v252, 28
	v_readlane_b32 s73, v252, 29
	s_waitcnt vmcnt(0)
	v_pk_add_f32 v[30:31], v[200:201], v[30:31]
	v_pk_add_f32 v[28:29], v[202:203], v[28:29]
	v_pk_add_f32 v[42:43], v[204:205], v[42:43]
	v_pk_add_f32 v[40:41], v[206:207], v[40:41]
	v_pk_add_f32 v[54:55], v[210:211], v[54:55]
	v_pk_add_f32 v[52:53], v[208:209], v[52:53]
	v_mul_f32_e32 v234, v29, v29
	v_mul_f32_e32 v235, v31, v31
	v_pk_mul_f32 v[200:201], v[14:15], v[30:31]
	v_pk_mul_f32 v[202:203], v[12:13], v[28:29]
	v_mul_f32_e32 v236, v41, v41
	v_mul_f32_e32 v237, v43, v43
	global_store_dwordx4 v[228:229], v[28:31], off
	v_pk_mul_f32 v[204:205], v[10:11], v[42:43]
	v_pk_mul_f32 v[206:207], v[8:9], v[40:41]
	v_mul_f32_e32 v238, v53, v53
	v_mul_f32_e32 v239, v55, v55
	v_fmac_f32_e32 v234, v28, v28
	v_fmac_f32_e32 v235, v30, v30
	v_cvt_pk_bf16_f32 v28, v202, v203
	v_cvt_pk_bf16_f32 v29, v200, v201
	v_fmac_f32_e32 v236, v40, v40
	v_fmac_f32_e32 v237, v42, v42
	v_cvt_pk_bf16_f32 v30, v206, v207
	v_cvt_pk_bf16_f32 v31, v204, v205
	v_fmac_f32_e32 v238, v52, v52
	v_fmac_f32_e32 v239, v54, v54
	v_add_f32_e32 v200, v234, v235
	v_mov_b32_e32 v242, v28
	v_mov_b32_e32 v243, v29
	global_store_dwordx4 v[228:229], v[40:43], off offset:64
	v_add_f32_e32 v28, v236, v237
	v_pk_mul_f32 v[208:209], v[6:7], v[54:55]
	v_pk_mul_f32 v[210:211], v[4:5], v[52:53]
	v_mov_b32_e32 v244, v30
	v_mov_b32_e32 v245, v31
	s_nop 1
	v_permlane16_swap_b32_e32 v242, v244
	v_permlane16_swap_b32_e32 v243, v245
	global_store_dwordx4 v[232:233], v[242:245], off
	global_store_dwordx4 v[228:229], v[52:55], off offset:512
	v_add_f32_e32 v29, v238, v239
	v_add_f32_e32 v28, v200, v28
	v_or_b32_e32 v30, 0x100, v226
	v_mov_b32_e32 v31, v227
	v_add_f32_e32 v40, v28, v29
	v_cvt_pk_bf16_f32 v28, v210, v211
	v_cvt_pk_bf16_f32 v29, v208, v209
	v_lshl_add_u64 v[30:31], s[12:13], 0, v[30:31]
	v_mov_b32_e32 v246, v28
	v_mov_b32_e32 v247, v29
	v_pk_add_f32 v[30:31], v[198:199], v[62:63]
	v_pk_add_f32 v[28:29], v[196:197], v[60:61]
	v_mul_f32_e32 v42, v31, v31
	v_mul_f32_e32 v41, v29, v29
	v_fmac_f32_e32 v41, v28, v28
	v_fmac_f32_e32 v42, v30, v30
	v_add_f32_e32 v41, v41, v42
	v_add_f32_e32 v41, v40, v41
	ds_bpermute_b32 v42, v225, v41
	global_store_dwordx4 v[228:229], v[28:31], off offset:576
	v_or_b32_e32 v226, 0x100, v226
	s_nop 0
	v_pk_mul_f32 v[28:29], v[0:1], v[28:29]
	v_pk_mul_f32 v[30:31], v[2:3], v[30:31]
	v_cvt_pk_bf16_f32 v40, v28, v29
	s_waitcnt lgkmcnt(0)
	v_add_f32_e32 v28, v41, v42
	ds_bpermute_b32 v29, v224, v28
	v_cvt_pk_bf16_f32 v41, v30, v31
	v_lshl_add_u64 v[30:31], s[12:13], 0, v[226:227]
	v_mov_b32_e32 v248, v40
	v_mov_b32_e32 v249, v41
	s_nop 1
	v_permlane16_swap_b32_e32 v246, v248
	v_permlane16_swap_b32_e32 v247, v249
	global_store_dwordx4 v[30:31], v[246:249], off
	s_and_saveexec_b64 s[24:25], s[4:5]
	s_cbranch_execz .LBB0_234
	v_lshl_add_u64 v[30:31], v[64:65], 2, s[14:15]
	s_waitcnt lgkmcnt(0)
	v_add_f32_e32 v28, v28, v29
	global_atomic_add_f32 v[30:31], v28, off
.LBB0_234:
	s_or_b64 exec, exec, s[24:25]
	v_or_b32_e32 v196, 48, v64
	v_ashrrev_i32_e32 v197, 31, v196
	v_readlane_b32 s60, v252, 0
	s_waitcnt lgkmcnt(0)
	v_lshlrev_b64 v[28:29], 13, v[196:197]
	v_readlane_b32 s61, v252, 1
	v_readlane_b32 s62, v252, 2
	v_readlane_b32 s63, v252, 3
	v_lshl_add_u64 v[28:29], s[60:61], 0, v[28:29]
	v_lshl_add_u64 v[28:29], v[140:141], 2, v[28:29]
	global_load_dwordx4 v[60:63], v[28:29], off
	global_load_dwordx4 v[52:55], v[28:29], off offset:64
	global_load_dwordx4 v[40:43], v[28:29], off offset:512
	s_nop 0
	global_load_dwordx4 v[28:31], v[28:29], off offset:576
	v_readlane_b32 s64, v252, 4
	v_readlane_b32 s65, v252, 5
	v_readlane_b32 s66, v252, 6
	v_readlane_b32 s67, v252, 7
	v_readlane_b32 s68, v252, 8
	v_readlane_b32 s69, v252, 9
	v_readlane_b32 s70, v252, 10
	v_readlane_b32 s71, v252, 11
	v_readlane_b32 s72, v252, 12
	v_readlane_b32 s73, v252, 13
	v_readlane_b32 s74, v252, 14
	v_readlane_b32 s75, v252, 15
	v_lshlrev_b64 v[198:199], 11, v[66:67]
	v_readlane_b32 s60, v252, 16
	v_lshl_add_u64 v[198:199], v[198:199], 0, v[140:141]
	v_pk_add_f32 v[58:59], v[194:195], v[58:59]
	v_pk_add_f32 v[56:57], v[192:193], v[56:57]
	v_readlane_b32 s74, v252, 30
	v_readlane_b32 s75, v252, 31
	v_mul_f32_e32 v65, v57, v57
	v_mul_f32_e32 v194, v59, v59
	v_lshl_add_u64 v[192:193], v[198:199], 2, s[74:75]
	global_store_dwordx4 v[192:193], v[56:59], off
	v_fmac_f32_e32 v65, v56, v56
	v_fmac_f32_e32 v194, v58, v58
	v_pk_mul_f32 v[58:59], v[14:15], v[58:59]
	v_pk_mul_f32 v[56:57], v[12:13], v[56:57]
	v_add_f32_e32 v65, v65, v194
	v_cvt_pk_bf16_f32 v56, v56, v57
	v_cvt_pk_bf16_f32 v57, v58, v59
	v_lshlrev_b64 v[58:59], 1, v[198:199]
	v_add_u32_e32 v58, v58, v253
	v_lshl_add_u64 v[194:195], s[12:13], 0, v[58:59]
	v_pk_add_f32 v[50:51], v[190:191], v[50:51]
	v_pk_add_f32 v[48:49], v[188:189], v[48:49]
	v_mov_b32_e32 v242, v56
	v_mov_b32_e32 v243, v57
	v_mul_f32_e32 v56, v49, v49
	v_mul_f32_e32 v57, v51, v51
	global_store_dwordx4 v[192:193], v[48:51], off offset:64
	v_fmac_f32_e32 v56, v48, v48
	v_fmac_f32_e32 v57, v50, v50
	v_pk_mul_f32 v[50:51], v[10:11], v[50:51]
	v_pk_mul_f32 v[48:49], v[8:9], v[48:49]
	v_pk_add_f32 v[38:39], v[186:187], v[38:39]
	v_cvt_pk_bf16_f32 v48, v48, v49
	v_cvt_pk_bf16_f32 v49, v50, v51
	v_or_b32_e32 v50, 0, v58
	v_mov_b32_e32 v51, v59
	v_lshl_add_u64 v[50:51], s[12:13], 0, v[50:51]
	v_pk_add_f32 v[36:37], v[184:185], v[36:37]
	v_mov_b32_e32 v244, v48
	v_mov_b32_e32 v245, v49
	s_nop 1
	v_permlane16_swap_b32_e32 v242, v244
	v_permlane16_swap_b32_e32 v243, v245
	global_store_dwordx4 v[50:51], v[242:245], off
	v_mul_f32_e32 v48, v37, v37
	v_mul_f32_e32 v49, v39, v39
	global_store_dwordx4 v[192:193], v[36:39], off offset:512
	v_fmac_f32_e32 v48, v36, v36
	v_fmac_f32_e32 v49, v38, v38
	v_pk_mul_f32 v[38:39], v[6:7], v[38:39]
	v_pk_mul_f32 v[36:37], v[4:5], v[36:37]
	v_pk_add_f32 v[26:27], v[182:183], v[26:27]
	v_cvt_pk_bf16_f32 v36, v36, v37
	v_cvt_pk_bf16_f32 v37, v38, v39
	v_or_b32_e32 v38, 0x100, v58
	v_mov_b32_e32 v39, v59
	v_lshl_add_u64 v[38:39], s[12:13], 0, v[38:39]
	v_pk_add_f32 v[24:25], v[180:181], v[24:25]
	v_add_f32_e32 v56, v56, v57
	v_mov_b32_e32 v246, v36
	v_mov_b32_e32 v247, v37
	v_mul_f32_e32 v36, v25, v25
	v_mul_f32_e32 v37, v27, v27
	v_add_f32_e32 v56, v65, v56
	v_add_f32_e32 v48, v48, v49
	v_fmac_f32_e32 v36, v24, v24
	v_fmac_f32_e32 v37, v26, v26
	v_add_f32_e32 v48, v56, v48
	v_add_f32_e32 v36, v36, v37
	v_add_f32_e32 v37, v48, v36
	ds_bpermute_b32 v38, v225, v37
	global_store_dwordx4 v[192:193], v[24:27], off offset:576
	v_or_b32_e32 v58, 0x100, v58
	v_readlane_b32 s61, v252, 17
	v_pk_mul_f32 v[24:25], v[0:1], v[24:25]
	v_pk_mul_f32 v[26:27], v[2:3], v[26:27]
	v_cvt_pk_bf16_f32 v36, v24, v25
	s_waitcnt lgkmcnt(0)
	v_add_f32_e32 v24, v37, v38
	ds_bpermute_b32 v25, v224, v24
	v_cvt_pk_bf16_f32 v37, v26, v27
	v_lshl_add_u64 v[26:27], s[12:13], 0, v[58:59]
	v_readlane_b32 s62, v252, 18
	v_readlane_b32 s63, v252, 19
	v_readlane_b32 s64, v252, 20
	v_readlane_b32 s65, v252, 21
	v_readlane_b32 s66, v252, 22
	v_readlane_b32 s67, v252, 23
	v_readlane_b32 s68, v252, 24
	v_readlane_b32 s69, v252, 25
	v_readlane_b32 s70, v252, 26
	v_readlane_b32 s71, v252, 27
	v_readlane_b32 s72, v252, 28
	v_readlane_b32 s73, v252, 29
	v_mov_b32_e32 v248, v36
	v_mov_b32_e32 v249, v37
	s_nop 1
	v_permlane16_swap_b32_e32 v246, v248
	v_permlane16_swap_b32_e32 v247, v249
	global_store_dwordx4 v[26:27], v[246:249], off
	s_and_saveexec_b64 s[24:25], s[4:5]
	s_cbranch_execz .LBB0_236
	v_lshl_add_u64 v[26:27], v[66:67], 2, s[14:15]
	s_waitcnt lgkmcnt(0)
	v_add_f32_e32 v24, v24, v25
	global_atomic_add_f32 v[26:27], v24, off
.LBB0_236:
	s_or_b64 exec, exec, s[24:25]
	v_add_u32_e32 v180, 0x80, v64
	v_ashrrev_i32_e32 v181, 31, v180
	v_readlane_b32 s60, v252, 0
	s_waitcnt lgkmcnt(0)
	v_lshlrev_b64 v[24:25], 13, v[180:181]
	v_readlane_b32 s61, v252, 1
	v_readlane_b32 s62, v252, 2
	v_readlane_b32 s63, v252, 3
	v_lshl_add_u64 v[24:25], s[60:61], 0, v[24:25]
	v_lshl_add_u64 v[24:25], v[140:141], 2, v[24:25]
	global_load_dwordx4 v[64:67], v[24:25], off
	global_load_dwordx4 v[48:51], v[24:25], off offset:64
	global_load_dwordx4 v[36:39], v[24:25], off offset:512
	s_nop 0
	global_load_dwordx4 v[24:27], v[24:25], off offset:576
	v_readlane_b32 s64, v252, 4
	v_readlane_b32 s65, v252, 5
	v_readlane_b32 s66, v252, 6
	v_readlane_b32 s67, v252, 7
	v_readlane_b32 s68, v252, 8
	v_readlane_b32 s69, v252, 9
	v_readlane_b32 s70, v252, 10
	v_readlane_b32 s71, v252, 11
	v_readlane_b32 s72, v252, 12
	v_readlane_b32 s73, v252, 13
	v_readlane_b32 s74, v252, 14
	v_readlane_b32 s75, v252, 15
	v_lshlrev_b64 v[56:57], 11, v[214:215]
	v_readlane_b32 s60, v252, 16
	v_lshl_add_u64 v[56:57], v[56:57], 0, v[140:141]
	v_pk_add_f32 v[46:47], v[178:179], v[46:47]
	v_pk_add_f32 v[44:45], v[176:177], v[44:45]
	v_readlane_b32 s74, v252, 30
	v_readlane_b32 s75, v252, 31
	v_mul_f32_e32 v176, v45, v45
	v_mul_f32_e32 v177, v47, v47
	v_lshl_add_u64 v[58:59], v[56:57], 2, s[74:75]
	global_store_dwordx4 v[58:59], v[44:47], off
	v_fmac_f32_e32 v176, v44, v44
	v_fmac_f32_e32 v177, v46, v46
	v_pk_mul_f32 v[46:47], v[14:15], v[46:47]
	v_pk_mul_f32 v[44:45], v[12:13], v[44:45]
	v_pk_add_f32 v[34:35], v[174:175], v[34:35]
	v_cvt_pk_bf16_f32 v44, v44, v45
	v_cvt_pk_bf16_f32 v45, v46, v47
	v_lshlrev_b64 v[46:47], 1, v[56:57]
	v_add_u32_e32 v46, v46, v253
	v_lshl_add_u64 v[56:57], s[12:13], 0, v[46:47]
	v_pk_add_f32 v[32:33], v[172:173], v[32:33]
	v_mov_b32_e32 v242, v44
	v_mov_b32_e32 v243, v45
	v_mul_f32_e32 v44, v33, v33
	v_mul_f32_e32 v45, v35, v35
	global_store_dwordx4 v[58:59], v[32:35], off offset:64
	v_fmac_f32_e32 v44, v32, v32
	v_fmac_f32_e32 v45, v34, v34
	v_pk_mul_f32 v[34:35], v[10:11], v[34:35]
	v_pk_mul_f32 v[32:33], v[8:9], v[32:33]
	v_pk_add_f32 v[22:23], v[170:171], v[22:23]
	v_cvt_pk_bf16_f32 v32, v32, v33
	v_cvt_pk_bf16_f32 v33, v34, v35
	v_or_b32_e32 v34, 0, v46
	v_mov_b32_e32 v35, v47
	v_lshl_add_u64 v[34:35], s[12:13], 0, v[34:35]
	v_pk_add_f32 v[20:21], v[168:169], v[20:21]
	v_mov_b32_e32 v244, v32
	v_mov_b32_e32 v245, v33
	s_nop 1
	v_permlane16_swap_b32_e32 v242, v244
	v_permlane16_swap_b32_e32 v243, v245
	global_store_dwordx4 v[34:35], v[242:245], off
	v_mul_f32_e32 v32, v21, v21
	v_mul_f32_e32 v33, v23, v23
	global_store_dwordx4 v[58:59], v[20:23], off offset:512
	v_fmac_f32_e32 v32, v20, v20
	v_fmac_f32_e32 v33, v22, v22
	v_pk_mul_f32 v[22:23], v[6:7], v[22:23]
	v_pk_mul_f32 v[20:21], v[4:5], v[20:21]
	v_pk_add_f32 v[18:19], v[166:167], v[18:19]
	v_cvt_pk_bf16_f32 v20, v20, v21
	v_cvt_pk_bf16_f32 v21, v22, v23
	v_or_b32_e32 v22, 0x100, v46
	v_mov_b32_e32 v23, v47
	v_lshl_add_u64 v[22:23], s[12:13], 0, v[22:23]
	v_pk_add_f32 v[16:17], v[164:165], v[16:17]
	v_add_f32_e32 v176, v176, v177
	v_add_f32_e32 v44, v44, v45
	v_mov_b32_e32 v246, v20
	v_mov_b32_e32 v247, v21
	v_mul_f32_e32 v20, v17, v17
	v_mul_f32_e32 v21, v19, v19
	v_add_f32_e32 v44, v176, v44
	v_add_f32_e32 v32, v32, v33
	v_fmac_f32_e32 v20, v16, v16
	v_fmac_f32_e32 v21, v18, v18
	v_add_f32_e32 v32, v44, v32
	v_add_f32_e32 v20, v20, v21
	v_add_f32_e32 v21, v32, v20
	ds_bpermute_b32 v22, v225, v21
	global_store_dwordx4 v[58:59], v[16:19], off offset:576
	v_or_b32_e32 v46, 0x100, v46
	v_readlane_b32 s61, v252, 17
	v_pk_mul_f32 v[16:17], v[0:1], v[16:17]
	v_pk_mul_f32 v[18:19], v[2:3], v[18:19]
	v_cvt_pk_bf16_f32 v20, v16, v17
	s_waitcnt lgkmcnt(0)
	v_add_f32_e32 v16, v21, v22
	ds_bpermute_b32 v17, v224, v16
	v_cvt_pk_bf16_f32 v21, v18, v19
	v_lshl_add_u64 v[18:19], s[12:13], 0, v[46:47]
	v_readlane_b32 s62, v252, 18
	v_readlane_b32 s63, v252, 19
	v_readlane_b32 s64, v252, 20
	v_readlane_b32 s65, v252, 21
	v_readlane_b32 s66, v252, 22
	v_readlane_b32 s67, v252, 23
	v_readlane_b32 s68, v252, 24
	v_readlane_b32 s69, v252, 25
	v_readlane_b32 s70, v252, 26
	v_readlane_b32 s71, v252, 27
	v_readlane_b32 s72, v252, 28
	v_readlane_b32 s73, v252, 29
	v_mov_b32_e32 v248, v20
	v_mov_b32_e32 v249, v21
	s_nop 1
	v_permlane16_swap_b32_e32 v246, v248
	v_permlane16_swap_b32_e32 v247, v249
	global_store_dwordx4 v[18:19], v[246:249], off
	s_and_saveexec_b64 s[24:25], s[4:5]
	s_cbranch_execz .LBB0_238
	v_lshl_add_u64 v[18:19], v[214:215], 2, s[14:15]
	s_waitcnt lgkmcnt(0)
	v_add_f32_e32 v16, v16, v17
	global_atomic_add_f32 v[18:19], v16, off
.LBB0_238:
	s_or_b64 exec, exec, s[24:25]
	s_waitcnt lgkmcnt(0)
	v_lshl_add_u64 v[16:17], v[140:141], 2, v[212:213]
	v_lshl_add_u64 v[18:19], v[16:17], 0, s[20:21]
	v_add_co_u32_e32 v16, vcc, 0x120000, v16
	v_lshlrev_b64 v[20:21], 11, v[196:197]
	s_nop 0
	v_addc_co_u32_e32 v17, vcc, 0, v17, vcc
	global_load_dwordx4 v[44:47], v[18:19], off offset:64
	global_load_dwordx4 v[32:35], v[18:19], off offset:512
	global_load_dwordx4 v[56:59], v[16:17], off
	s_nop 0
	global_load_dwordx4 v[16:19], v[18:19], off offset:576
	v_lshl_add_u64 v[164:165], v[20:21], 0, v[140:141]
	s_waitcnt vmcnt(23)
	v_pk_add_f32 v[22:23], v[160:161], v[62:63]
	v_pk_add_f32 v[20:21], v[158:159], v[60:61]
	v_readlane_b32 s60, v252, 16
	v_readlane_b32 s74, v252, 30
	v_readlane_b32 s75, v252, 31
	v_mul_f32_e32 v62, v21, v21
	v_mul_f32_e32 v63, v23, v23
	v_lshl_add_u64 v[60:61], v[164:165], 2, s[74:75]
	v_fmac_f32_e32 v62, v20, v20
	v_fmac_f32_e32 v63, v22, v22
	global_store_dwordx4 v[60:61], v[20:23], off
	v_add_f32_e32 v158, v62, v63
	v_lshlrev_b64 v[62:63], 1, v[164:165]
	v_add_u32_e32 v62, v62, v253
	v_pk_mul_f32 v[22:23], v[14:15], v[22:23]
	v_pk_mul_f32 v[20:21], v[12:13], v[20:21]
	v_readlane_b32 s61, v252, 17
	v_cvt_pk_bf16_f32 v20, v20, v21
	v_cvt_pk_bf16_f32 v21, v22, v23
	v_lshl_add_u64 v[22:23], s[12:13], 0, v[62:63]
	v_mov_b32_e32 v242, v20
	v_mov_b32_e32 v243, v21
	s_waitcnt vmcnt(23)
	v_pk_add_f32 v[22:23], v[156:157], v[54:55]
	v_pk_add_f32 v[20:21], v[154:155], v[52:53]
	v_mul_f32_e32 v53, v23, v23
	v_mul_f32_e32 v52, v21, v21
	global_store_dwordx4 v[60:61], v[20:23], off offset:64
	v_fmac_f32_e32 v52, v20, v20
	v_fmac_f32_e32 v53, v22, v22
	v_pk_mul_f32 v[22:23], v[10:11], v[22:23]
	v_pk_mul_f32 v[20:21], v[8:9], v[20:21]
	v_add_f32_e32 v52, v52, v53
	v_cvt_pk_bf16_f32 v20, v20, v21
	v_cvt_pk_bf16_f32 v21, v22, v23
	v_or_b32_e32 v22, 0, v62
	v_mov_b32_e32 v23, v63
	v_lshl_add_u64 v[22:23], s[12:13], 0, v[22:23]
	v_mov_b32_e32 v244, v20
	v_mov_b32_e32 v245, v21
	s_nop 1
	v_permlane16_swap_b32_e32 v242, v244
	v_permlane16_swap_b32_e32 v243, v245
	global_store_dwordx4 v[22:23], v[242:245], off
	s_waitcnt vmcnt(24)
	v_pk_add_f32 v[22:23], v[152:153], v[42:43]
	v_pk_add_f32 v[20:21], v[150:151], v[40:41]
	v_mul_f32_e32 v41, v23, v23
	v_mul_f32_e32 v40, v21, v21
	global_store_dwordx4 v[60:61], v[20:23], off offset:512
	v_fmac_f32_e32 v40, v20, v20
	v_fmac_f32_e32 v41, v22, v22
	v_pk_mul_f32 v[22:23], v[6:7], v[22:23]
	v_pk_mul_f32 v[20:21], v[4:5], v[20:21]
	v_add_f32_e32 v52, v158, v52
	v_cvt_pk_bf16_f32 v20, v20, v21
	v_cvt_pk_bf16_f32 v21, v22, v23
	v_or_b32_e32 v22, 0x100, v62
	v_mov_b32_e32 v23, v63
	v_lshl_add_u64 v[22:23], s[12:13], 0, v[22:23]
	v_mov_b32_e32 v246, v20
	v_mov_b32_e32 v247, v21
	s_waitcnt vmcnt(24)
	v_pk_add_f32 v[22:23], v[148:149], v[30:31]
	v_pk_add_f32 v[20:21], v[146:147], v[28:29]
	v_mul_f32_e32 v29, v23, v23
	v_mul_f32_e32 v28, v21, v21
	v_add_f32_e32 v40, v40, v41
	v_fmac_f32_e32 v28, v20, v20
	v_fmac_f32_e32 v29, v22, v22
	v_add_f32_e32 v40, v52, v40
	v_add_f32_e32 v28, v28, v29
	v_add_f32_e32 v29, v40, v28
	ds_bpermute_b32 v30, v225, v29
	global_store_dwordx4 v[60:61], v[20:23], off offset:576
	v_or_b32_e32 v62, 0x100, v62
	v_readlane_b32 s62, v252, 18
	v_pk_mul_f32 v[20:21], v[0:1], v[20:21]
	v_pk_mul_f32 v[22:23], v[2:3], v[22:23]
	v_cvt_pk_bf16_f32 v28, v20, v21
	s_waitcnt lgkmcnt(0)
	v_add_f32_e32 v20, v29, v30
	ds_bpermute_b32 v21, v224, v20
	v_cvt_pk_bf16_f32 v29, v22, v23
	v_lshl_add_u64 v[22:23], s[12:13], 0, v[62:63]
	v_readlane_b32 s63, v252, 19
	v_readlane_b32 s64, v252, 20
	v_readlane_b32 s65, v252, 21
	v_readlane_b32 s66, v252, 22
	v_readlane_b32 s67, v252, 23
	v_readlane_b32 s68, v252, 24
	v_readlane_b32 s69, v252, 25
	v_readlane_b32 s70, v252, 26
	v_readlane_b32 s71, v252, 27
	v_readlane_b32 s72, v252, 28
	v_readlane_b32 s73, v252, 29
	v_mov_b32_e32 v248, v28
	v_mov_b32_e32 v249, v29
	s_nop 1
	v_permlane16_swap_b32_e32 v246, v248
	v_permlane16_swap_b32_e32 v247, v249
	global_store_dwordx4 v[22:23], v[246:249], off
	s_and_saveexec_b64 s[24:25], s[4:5]
	s_cbranch_execz .LBB0_240
	v_lshl_add_u64 v[22:23], v[196:197], 2, s[14:15]
	s_waitcnt lgkmcnt(0)
	v_add_f32_e32 v20, v20, v21
	global_atomic_add_f32 v[22:23], v20, off
.LBB0_240:
	s_or_b64 exec, exec, s[24:25]
	v_or_b32_e32 v146, 32, v180
	v_ashrrev_i32_e32 v147, 31, v146
	v_readlane_b32 s60, v252, 0
	s_waitcnt lgkmcnt(0)
	v_lshlrev_b64 v[20:21], 13, v[146:147]
	v_readlane_b32 s61, v252, 1
	v_readlane_b32 s62, v252, 2
	v_readlane_b32 s63, v252, 3
	v_lshl_add_u64 v[20:21], s[60:61], 0, v[20:21]
	v_lshl_add_u64 v[20:21], v[140:141], 2, v[20:21]
	global_load_dwordx4 v[52:55], v[20:21], off
	global_load_dwordx4 v[40:43], v[20:21], off offset:64
	global_load_dwordx4 v[28:31], v[20:21], off offset:512
	s_nop 0
	global_load_dwordx4 v[20:23], v[20:21], off offset:576
	v_readlane_b32 s64, v252, 4
	v_readlane_b32 s65, v252, 5
	v_readlane_b32 s66, v252, 6
	v_readlane_b32 s67, v252, 7
	v_readlane_b32 s68, v252, 8
	v_readlane_b32 s69, v252, 9
	v_readlane_b32 s70, v252, 10
	v_readlane_b32 s71, v252, 11
	v_readlane_b32 s72, v252, 12
	v_readlane_b32 s73, v252, 13
	v_readlane_b32 s74, v252, 14
	v_readlane_b32 s75, v252, 15
	v_lshlrev_b64 v[60:61], 11, v[180:181]
	v_readlane_b32 s60, v252, 16
	v_lshl_add_u64 v[148:149], v[60:61], 0, v[140:141]
	s_waitcnt vmcnt(23)
	v_pk_add_f32 v[62:63], v[144:145], v[66:67]
	v_pk_add_f32 v[60:61], v[142:143], v[64:65]
	v_readlane_b32 s74, v252, 30
	v_readlane_b32 s75, v252, 31
	v_mul_f32_e32 v66, v61, v61
	v_mul_f32_e32 v67, v63, v63
	v_lshl_add_u64 v[64:65], v[148:149], 2, s[74:75]
	global_store_dwordx4 v[64:65], v[60:63], off
	v_fmac_f32_e32 v66, v60, v60
	v_fmac_f32_e32 v67, v62, v62
	v_pk_mul_f32 v[62:63], v[14:15], v[62:63]
	v_pk_mul_f32 v[60:61], v[12:13], v[60:61]
	v_add_f32_e32 v142, v66, v67
	v_cvt_pk_bf16_f32 v60, v60, v61
	v_cvt_pk_bf16_f32 v61, v62, v63
	v_lshlrev_b64 v[62:63], 1, v[148:149]
	v_add_u32_e32 v62, v62, v253
	v_lshl_add_u64 v[66:67], s[12:13], 0, v[62:63]
	s_waitcnt vmcnt(23)
	v_pk_add_f32 v[50:51], v[126:127], v[50:51]
	v_pk_add_f32 v[48:49], v[124:125], v[48:49]
	v_mov_b32_e32 v242, v60
	v_mov_b32_e32 v243, v61
	v_mul_f32_e32 v60, v49, v49
	v_mul_f32_e32 v61, v51, v51
	global_store_dwordx4 v[64:65], v[48:51], off offset:64
	v_fmac_f32_e32 v60, v48, v48
	v_fmac_f32_e32 v61, v50, v50
	v_pk_mul_f32 v[50:51], v[10:11], v[50:51]
	v_pk_mul_f32 v[48:49], v[8:9], v[48:49]
	s_waitcnt vmcnt(23)
	v_pk_add_f32 v[38:39], v[122:123], v[38:39]
	v_cvt_pk_bf16_f32 v48, v48, v49
	v_cvt_pk_bf16_f32 v49, v50, v51
	v_or_b32_e32 v50, 0, v62
	v_mov_b32_e32 v51, v63
	v_lshl_add_u64 v[50:51], s[12:13], 0, v[50:51]
	v_pk_add_f32 v[36:37], v[120:121], v[36:37]
	v_mov_b32_e32 v244, v48
	v_mov_b32_e32 v245, v49
	s_nop 1
	v_permlane16_swap_b32_e32 v242, v244
	v_permlane16_swap_b32_e32 v243, v245
	global_store_dwordx4 v[50:51], v[242:245], off
	v_mul_f32_e32 v48, v37, v37
	v_mul_f32_e32 v49, v39, v39
	global_store_dwordx4 v[64:65], v[36:39], off offset:512
	v_fmac_f32_e32 v48, v36, v36
	v_fmac_f32_e32 v49, v38, v38
	v_pk_mul_f32 v[38:39], v[6:7], v[38:39]
	v_pk_mul_f32 v[36:37], v[4:5], v[36:37]
	s_waitcnt vmcnt(24)
	v_pk_add_f32 v[26:27], v[118:119], v[26:27]
	v_cvt_pk_bf16_f32 v36, v36, v37
	v_cvt_pk_bf16_f32 v37, v38, v39
	v_or_b32_e32 v38, 0x100, v62
	v_mov_b32_e32 v39, v63
	v_lshl_add_u64 v[38:39], s[12:13], 0, v[38:39]
	v_pk_add_f32 v[24:25], v[116:117], v[24:25]
	v_add_f32_e32 v60, v60, v61
	v_mov_b32_e32 v246, v36
	v_mov_b32_e32 v247, v37
	v_mul_f32_e32 v36, v25, v25
	v_mul_f32_e32 v37, v27, v27
	v_add_f32_e32 v60, v142, v60
	v_add_f32_e32 v48, v48, v49
	v_fmac_f32_e32 v36, v24, v24
	v_fmac_f32_e32 v37, v26, v26
	v_add_f32_e32 v48, v60, v48
	v_add_f32_e32 v36, v36, v37
	v_add_f32_e32 v37, v48, v36
	ds_bpermute_b32 v38, v225, v37
	global_store_dwordx4 v[64:65], v[24:27], off offset:576
	v_or_b32_e32 v62, 0x100, v62
	v_readlane_b32 s61, v252, 17
	v_pk_mul_f32 v[24:25], v[0:1], v[24:25]
	v_pk_mul_f32 v[26:27], v[2:3], v[26:27]
	v_cvt_pk_bf16_f32 v36, v24, v25
	s_waitcnt lgkmcnt(0)
	v_add_f32_e32 v24, v37, v38
	ds_bpermute_b32 v25, v224, v24
	v_cvt_pk_bf16_f32 v37, v26, v27
	v_lshl_add_u64 v[26:27], s[12:13], 0, v[62:63]
	v_readlane_b32 s62, v252, 18
	v_readlane_b32 s63, v252, 19
	v_readlane_b32 s64, v252, 20
	v_readlane_b32 s65, v252, 21
	v_readlane_b32 s66, v252, 22
	v_readlane_b32 s67, v252, 23
	v_readlane_b32 s68, v252, 24
	v_readlane_b32 s69, v252, 25
	v_readlane_b32 s70, v252, 26
	v_readlane_b32 s71, v252, 27
	v_readlane_b32 s72, v252, 28
	v_readlane_b32 s73, v252, 29
	v_mov_b32_e32 v248, v36
	v_mov_b32_e32 v249, v37
	s_nop 1
	v_permlane16_swap_b32_e32 v246, v248
	v_permlane16_swap_b32_e32 v247, v249
	global_store_dwordx4 v[26:27], v[246:249], off
	s_and_saveexec_b64 s[24:25], s[4:5]
	s_cbranch_execz .LBB0_242
	v_lshl_add_u64 v[26:27], v[180:181], 2, s[14:15]
	s_waitcnt lgkmcnt(0)
	v_add_f32_e32 v24, v24, v25
	global_atomic_add_f32 v[26:27], v24, off
.LBB0_242:
	s_or_b64 exec, exec, s[24:25]
	v_or_b32_e32 v64, 48, v180
	v_ashrrev_i32_e32 v65, 31, v64
	v_readlane_b32 s60, v252, 0
	s_waitcnt lgkmcnt(0)
	v_lshlrev_b64 v[24:25], 13, v[64:65]
	v_readlane_b32 s61, v252, 1
	v_or_b32_e32 v66, 16, v180
	v_readlane_b32 s62, v252, 2
	v_lshl_add_u64 v[24:25], s[60:61], 0, v[24:25]
	v_lshl_add_u64 v[24:25], v[140:141], 2, v[24:25]
	global_load_dwordx4 v[60:63], v[24:25], off
	global_load_dwordx4 v[48:51], v[24:25], off offset:64
	global_load_dwordx4 v[36:39], v[24:25], off offset:512
	s_nop 0
	global_load_dwordx4 v[24:27], v[24:25], off offset:576
	v_readlane_b32 s63, v252, 3
	v_readlane_b32 s64, v252, 4
	v_readlane_b32 s65, v252, 5
	v_readlane_b32 s66, v252, 6
	v_readlane_b32 s67, v252, 7
	v_readlane_b32 s68, v252, 8
	v_readlane_b32 s69, v252, 9
	v_readlane_b32 s70, v252, 10
	v_readlane_b32 s71, v252, 11
	v_readlane_b32 s72, v252, 12
	v_readlane_b32 s73, v252, 13
	v_readlane_b32 s74, v252, 14
	v_readlane_b32 s75, v252, 15
	v_ashrrev_i32_e32 v67, 31, v66
	v_lshlrev_b64 v[116:117], 11, v[66:67]
	v_readlane_b32 s60, v252, 16
	v_lshl_add_u64 v[116:117], v[116:117], 0, v[140:141]
	s_waitcnt vmcnt(21)
	v_pk_add_f32 v[58:59], v[114:115], v[58:59]
	v_pk_add_f32 v[56:57], v[112:113], v[56:57]
	v_readlane_b32 s74, v252, 30
	v_readlane_b32 s75, v252, 31
	v_mul_f32_e32 v114, v57, v57
	v_mul_f32_e32 v115, v59, v59
	v_lshl_add_u64 v[112:113], v[116:117], 2, s[74:75]
	global_store_dwordx4 v[112:113], v[56:59], off
	v_fmac_f32_e32 v114, v56, v56
	v_fmac_f32_e32 v115, v58, v58
	v_pk_mul_f32 v[58:59], v[14:15], v[58:59]
	v_pk_mul_f32 v[56:57], v[12:13], v[56:57]
	v_add_f32_e32 v118, v114, v115
	v_cvt_pk_bf16_f32 v56, v56, v57
	v_cvt_pk_bf16_f32 v57, v58, v59
	v_lshlrev_b64 v[58:59], 1, v[116:117]
	v_add_u32_e32 v58, v58, v253
	v_lshl_add_u64 v[114:115], s[12:13], 0, v[58:59]
	v_pk_add_f32 v[46:47], v[110:111], v[46:47]
	v_pk_add_f32 v[44:45], v[108:109], v[44:45]
	v_mov_b32_e32 v242, v56
	v_mov_b32_e32 v243, v57
	v_mul_f32_e32 v56, v45, v45
	v_mul_f32_e32 v57, v47, v47
	global_store_dwordx4 v[112:113], v[44:47], off offset:64
	v_fmac_f32_e32 v56, v44, v44
	v_fmac_f32_e32 v57, v46, v46
	v_pk_mul_f32 v[46:47], v[10:11], v[46:47]
	v_pk_mul_f32 v[44:45], v[8:9], v[44:45]
	v_pk_add_f32 v[34:35], v[106:107], v[34:35]
	v_cvt_pk_bf16_f32 v44, v44, v45
	v_cvt_pk_bf16_f32 v45, v46, v47
	v_or_b32_e32 v46, 0, v58
	v_mov_b32_e32 v47, v59
	v_lshl_add_u64 v[46:47], s[12:13], 0, v[46:47]
	v_pk_add_f32 v[32:33], v[104:105], v[32:33]
	v_mov_b32_e32 v244, v44
	v_mov_b32_e32 v245, v45
	s_nop 1
	v_permlane16_swap_b32_e32 v242, v244
	v_permlane16_swap_b32_e32 v243, v245
	global_store_dwordx4 v[46:47], v[242:245], off
	v_mul_f32_e32 v44, v33, v33
	v_mul_f32_e32 v45, v35, v35
	global_store_dwordx4 v[112:113], v[32:35], off offset:512
	v_fmac_f32_e32 v44, v32, v32
	v_fmac_f32_e32 v45, v34, v34
	v_pk_mul_f32 v[34:35], v[6:7], v[34:35]
	v_pk_mul_f32 v[32:33], v[4:5], v[32:33]
	s_waitcnt vmcnt(24)
	v_pk_add_f32 v[18:19], v[102:103], v[18:19]
	v_cvt_pk_bf16_f32 v32, v32, v33
	v_cvt_pk_bf16_f32 v33, v34, v35
	v_or_b32_e32 v34, 0x100, v58
	v_mov_b32_e32 v35, v59
	v_lshl_add_u64 v[34:35], s[12:13], 0, v[34:35]
	v_pk_add_f32 v[16:17], v[100:101], v[16:17]
	v_add_f32_e32 v56, v56, v57
	v_mov_b32_e32 v246, v32
	v_mov_b32_e32 v247, v33
	v_mul_f32_e32 v32, v17, v17
	v_mul_f32_e32 v33, v19, v19
	v_add_f32_e32 v56, v118, v56
	v_add_f32_e32 v44, v44, v45
	v_fmac_f32_e32 v32, v16, v16
	v_fmac_f32_e32 v33, v18, v18
	v_add_f32_e32 v44, v56, v44
	v_add_f32_e32 v32, v32, v33
	v_add_f32_e32 v33, v44, v32
	ds_bpermute_b32 v34, v225, v33
	global_store_dwordx4 v[112:113], v[16:19], off offset:576
	v_or_b32_e32 v58, 0x100, v58
	v_readlane_b32 s61, v252, 17
	v_pk_mul_f32 v[16:17], v[0:1], v[16:17]
	v_pk_mul_f32 v[18:19], v[2:3], v[18:19]
	v_cvt_pk_bf16_f32 v32, v16, v17
	s_waitcnt lgkmcnt(0)
	v_add_f32_e32 v16, v33, v34
	ds_bpermute_b32 v17, v224, v16
	v_cvt_pk_bf16_f32 v33, v18, v19
	v_lshl_add_u64 v[18:19], s[12:13], 0, v[58:59]
	v_readlane_b32 s62, v252, 18
	v_readlane_b32 s63, v252, 19
	v_readlane_b32 s64, v252, 20
	v_readlane_b32 s65, v252, 21
	v_readlane_b32 s66, v252, 22
	v_readlane_b32 s67, v252, 23
	v_readlane_b32 s68, v252, 24
	v_readlane_b32 s69, v252, 25
	v_readlane_b32 s70, v252, 26
	v_readlane_b32 s71, v252, 27
	v_readlane_b32 s72, v252, 28
	v_readlane_b32 s73, v252, 29
	v_mov_b32_e32 v248, v32
	v_mov_b32_e32 v249, v33
	s_nop 1
	v_permlane16_swap_b32_e32 v246, v248
	v_permlane16_swap_b32_e32 v247, v249
	global_store_dwordx4 v[18:19], v[246:249], off
	s_and_saveexec_b64 s[24:25], s[4:5]
	s_cbranch_execz .LBB0_244
	v_lshl_add_u64 v[18:19], v[66:67], 2, s[14:15]
	s_waitcnt lgkmcnt(0)
	v_add_f32_e32 v16, v16, v17
	global_atomic_add_f32 v[18:19], v16, off
.LBB0_244:
	s_or_b64 exec, exec, s[24:25]
	s_waitcnt lgkmcnt(0)
	v_lshlrev_b64 v[16:17], 11, v[146:147]
	v_readlane_b32 s60, v252, 16
	v_lshl_add_u64 v[32:33], v[16:17], 0, v[140:141]
	s_waitcnt vmcnt(19)
	v_pk_add_f32 v[18:19], v[98:99], v[54:55]
	v_pk_add_f32 v[16:17], v[96:97], v[52:53]
	v_readlane_b32 s74, v252, 30
	v_readlane_b32 s75, v252, 31
	v_mul_f32_e32 v44, v17, v17
	v_mul_f32_e32 v45, v19, v19
	v_lshl_add_u64 v[34:35], v[32:33], 2, s[74:75]
	global_store_dwordx4 v[34:35], v[16:19], off
	v_fmac_f32_e32 v44, v16, v16
	v_fmac_f32_e32 v45, v18, v18
	v_pk_mul_f32 v[18:19], v[14:15], v[18:19]
	v_pk_mul_f32 v[16:17], v[12:13], v[16:17]
	v_lshlrev_b64 v[32:33], 1, v[32:33]
	v_add_u32_e32 v32, v32, v253
	v_cvt_pk_bf16_f32 v16, v16, v17
	v_cvt_pk_bf16_f32 v17, v18, v19
	v_lshl_add_u64 v[18:19], s[12:13], 0, v[32:33]
	v_mov_b32_e32 v242, v16
	v_mov_b32_e32 v243, v17
	s_waitcnt vmcnt(19)
	v_pk_add_f32 v[18:19], v[94:95], v[42:43]
	v_pk_add_f32 v[16:17], v[92:93], v[40:41]
	v_mul_f32_e32 v41, v19, v19
	v_mul_f32_e32 v40, v17, v17
	global_store_dwordx4 v[34:35], v[16:19], off offset:64
	v_fmac_f32_e32 v40, v16, v16
	v_fmac_f32_e32 v41, v18, v18
	v_pk_mul_f32 v[18:19], v[10:11], v[18:19]
	v_pk_mul_f32 v[16:17], v[8:9], v[16:17]
	v_add_f32_e32 v44, v44, v45
	v_cvt_pk_bf16_f32 v16, v16, v17
	v_cvt_pk_bf16_f32 v17, v18, v19
	v_or_b32_e32 v18, 0, v32
	v_mov_b32_e32 v19, v33
	v_lshl_add_u64 v[18:19], s[12:13], 0, v[18:19]
	v_mov_b32_e32 v244, v16
	v_mov_b32_e32 v245, v17
	s_nop 1
	v_permlane16_swap_b32_e32 v242, v244
	v_permlane16_swap_b32_e32 v243, v245
	global_store_dwordx4 v[18:19], v[242:245], off
	s_waitcnt vmcnt(20)
	v_pk_add_f32 v[18:19], v[90:91], v[30:31]
	v_pk_add_f32 v[16:17], v[88:89], v[28:29]
	v_mul_f32_e32 v29, v19, v19
	v_mul_f32_e32 v28, v17, v17
	global_store_dwordx4 v[34:35], v[16:19], off offset:512
	v_fmac_f32_e32 v28, v16, v16
	v_fmac_f32_e32 v29, v18, v18
	v_pk_mul_f32 v[18:19], v[6:7], v[18:19]
	v_pk_mul_f32 v[16:17], v[4:5], v[16:17]
	v_add_f32_e32 v40, v40, v41
	v_cvt_pk_bf16_f32 v16, v16, v17
	v_cvt_pk_bf16_f32 v17, v18, v19
	v_or_b32_e32 v18, 0x100, v32
	v_mov_b32_e32 v19, v33
	v_lshl_add_u64 v[18:19], s[12:13], 0, v[18:19]
	v_mov_b32_e32 v246, v16
	v_mov_b32_e32 v247, v17
	s_waitcnt vmcnt(20)
	v_pk_add_f32 v[18:19], v[86:87], v[22:23]
	v_pk_add_f32 v[16:17], v[84:85], v[20:21]
	v_mul_f32_e32 v21, v19, v19
	v_mul_f32_e32 v20, v17, v17
	v_add_f32_e32 v40, v44, v40
	v_add_f32_e32 v28, v28, v29
	v_fmac_f32_e32 v20, v16, v16
	v_fmac_f32_e32 v21, v18, v18
	v_add_f32_e32 v28, v40, v28
	v_add_f32_e32 v20, v20, v21
	v_add_f32_e32 v21, v28, v20
	ds_bpermute_b32 v22, v225, v21
	global_store_dwordx4 v[34:35], v[16:19], off offset:576
	v_or_b32_e32 v32, 0x100, v32
	v_readlane_b32 s61, v252, 17
	v_pk_mul_f32 v[16:17], v[0:1], v[16:17]
	v_pk_mul_f32 v[18:19], v[2:3], v[18:19]
	v_cvt_pk_bf16_f32 v20, v16, v17
	s_waitcnt lgkmcnt(0)
	v_add_f32_e32 v16, v21, v22
	ds_bpermute_b32 v17, v224, v16
	v_cvt_pk_bf16_f32 v21, v18, v19
	v_lshl_add_u64 v[18:19], s[12:13], 0, v[32:33]
	v_readlane_b32 s62, v252, 18
	v_readlane_b32 s63, v252, 19
	v_readlane_b32 s64, v252, 20
	v_readlane_b32 s65, v252, 21
	v_readlane_b32 s66, v252, 22
	v_readlane_b32 s67, v252, 23
	v_readlane_b32 s68, v252, 24
	v_readlane_b32 s69, v252, 25
	v_readlane_b32 s70, v252, 26
	v_readlane_b32 s71, v252, 27
	v_readlane_b32 s72, v252, 28
	v_readlane_b32 s73, v252, 29
	v_mov_b32_e32 v248, v20
	v_mov_b32_e32 v249, v21
	s_nop 1
	v_permlane16_swap_b32_e32 v246, v248
	v_permlane16_swap_b32_e32 v247, v249
	global_store_dwordx4 v[18:19], v[246:249], off
	s_and_saveexec_b64 s[24:25], s[4:5]
	s_cbranch_execz .LBB0_246
	v_lshl_add_u64 v[18:19], v[146:147], 2, s[14:15]
	s_waitcnt lgkmcnt(0)
	v_add_f32_e32 v16, v16, v17
	global_atomic_add_f32 v[18:19], v16, off
.LBB0_246:
	s_or_b64 exec, exec, s[24:25]
	s_waitcnt lgkmcnt(0)
	v_lshlrev_b64 v[16:17], 11, v[64:65]
	v_readlane_b32 s60, v252, 16
	v_lshl_add_u64 v[20:21], v[16:17], 0, v[140:141]
	s_waitcnt vmcnt(15)
	v_pk_add_f32 v[16:17], v[80:81], v[60:61]
	v_readlane_b32 s74, v252, 30
	v_readlane_b32 s75, v252, 31
	v_pk_add_f32 v[18:19], v[82:83], v[62:63]
	v_mul_f32_e32 v28, v17, v17
	v_lshl_add_u64 v[22:23], v[20:21], 2, s[74:75]
	global_store_dwordx4 v[22:23], v[16:19], off
	v_fmac_f32_e32 v28, v16, v16
	v_pk_mul_f32 v[14:15], v[14:15], v[18:19]
	v_pk_mul_f32 v[12:13], v[12:13], v[16:17]
	v_lshlrev_b64 v[16:17], 1, v[20:21]
	v_add_u32_e32 v16, v16, v253
	v_cvt_pk_bf16_f32 v12, v12, v13
	v_cvt_pk_bf16_f32 v13, v14, v15
	v_lshl_add_u64 v[14:15], s[12:13], 0, v[16:17]
	v_mov_b32_e32 v242, v12
	v_mov_b32_e32 v243, v13
	s_waitcnt vmcnt(15)
	v_pk_add_f32 v[14:15], v[78:79], v[50:51]
	v_pk_add_f32 v[12:13], v[76:77], v[48:49]
	v_pk_mul_f32 v[10:11], v[10:11], v[14:15]
	v_pk_mul_f32 v[8:9], v[8:9], v[12:13]
	global_store_dwordx4 v[22:23], v[12:15], off offset:64
	v_cvt_pk_bf16_f32 v8, v8, v9
	v_cvt_pk_bf16_f32 v9, v10, v11
	v_or_b32_e32 v10, 0, v16
	v_mov_b32_e32 v11, v17
	v_lshl_add_u64 v[10:11], s[12:13], 0, v[10:11]
	v_mov_b32_e32 v244, v8
	v_mov_b32_e32 v245, v9
	s_nop 1
	v_permlane16_swap_b32_e32 v242, v244
	v_permlane16_swap_b32_e32 v243, v245
	global_store_dwordx4 v[10:11], v[242:245], off
	s_waitcnt vmcnt(16)
	v_pk_add_f32 v[10:11], v[74:75], v[38:39]
	v_pk_add_f32 v[8:9], v[72:73], v[36:37]
	v_pk_mul_f32 v[6:7], v[6:7], v[10:11]
	v_pk_mul_f32 v[4:5], v[4:5], v[8:9]
	v_mul_f32_e32 v29, v19, v19
	v_cvt_pk_bf16_f32 v4, v4, v5
	v_cvt_pk_bf16_f32 v5, v6, v7
	v_or_b32_e32 v6, 0x100, v16
	v_mov_b32_e32 v7, v17
	v_fmac_f32_e32 v29, v18, v18
	v_mul_f32_e32 v18, v13, v13
	v_mul_f32_e32 v19, v15, v15
	v_lshl_add_u64 v[6:7], s[12:13], 0, v[6:7]
	v_fmac_f32_e32 v18, v12, v12
	v_fmac_f32_e32 v19, v14, v14
	global_store_dwordx4 v[22:23], v[8:11], off offset:512
	v_mul_f32_e32 v12, v9, v9
	v_mul_f32_e32 v13, v11, v11
	v_mov_b32_e32 v246, v4
	v_mov_b32_e32 v247, v5
	s_waitcnt vmcnt(16)
	v_pk_add_f32 v[6:7], v[70:71], v[26:27]
	v_pk_add_f32 v[4:5], v[68:69], v[24:25]
	v_add_f32_e32 v28, v28, v29
	v_add_f32_e32 v18, v18, v19
	v_fmac_f32_e32 v12, v8, v8
	v_fmac_f32_e32 v13, v10, v10
	v_mul_f32_e32 v8, v5, v5
	v_mul_f32_e32 v9, v7, v7
	v_add_f32_e32 v18, v28, v18
	v_add_f32_e32 v12, v12, v13
	v_fmac_f32_e32 v8, v4, v4
	v_fmac_f32_e32 v9, v6, v6
	v_add_f32_e32 v12, v18, v12
	v_add_f32_e32 v8, v8, v9
	v_add_f32_e32 v8, v12, v8
	ds_bpermute_b32 v9, v225, v8
	v_pk_mul_f32 v[0:1], v[0:1], v[4:5]
	global_store_dwordx4 v[22:23], v[4:7], off offset:576
	v_pk_mul_f32 v[2:3], v[2:3], v[6:7]
	v_or_b32_e32 v16, 0x100, v16
	v_cvt_pk_bf16_f32 v4, v0, v1
	s_waitcnt lgkmcnt(0)
	v_add_f32_e32 v0, v8, v9
	ds_bpermute_b32 v1, v224, v0
	v_cvt_pk_bf16_f32 v5, v2, v3
	v_lshl_add_u64 v[2:3], s[12:13], 0, v[16:17]
	v_readlane_b32 s61, v252, 17
	v_readlane_b32 s62, v252, 18
	v_readlane_b32 s63, v252, 19
	v_readlane_b32 s64, v252, 20
	v_readlane_b32 s65, v252, 21
	v_readlane_b32 s66, v252, 22
	v_readlane_b32 s67, v252, 23
	v_readlane_b32 s68, v252, 24
	v_readlane_b32 s69, v252, 25
	v_readlane_b32 s70, v252, 26
	v_readlane_b32 s71, v252, 27
	v_readlane_b32 s72, v252, 28
	v_readlane_b32 s73, v252, 29
	v_mov_b32_e32 v248, v4
	v_mov_b32_e32 v249, v5
	s_nop 1
	v_permlane16_swap_b32_e32 v246, v248
	v_permlane16_swap_b32_e32 v247, v249
	global_store_dwordx4 v[2:3], v[246:249], off
	s_and_saveexec_b64 s[24:25], s[4:5]
	s_cbranch_execz .LBB0_248
	v_lshl_add_u64 v[2:3], v[64:65], 2, s[14:15]
	s_waitcnt lgkmcnt(0)
	v_add_f32_e32 v0, v0, v1
	global_atomic_add_f32 v[2:3], v0, off

.LBB0_852:
	v_bfe_u32 v253, v220, 4, 1
	v_mul_u32_u24_e32 v253, 24, v253
	v_lshl_add_u32 v200, s54, 8, v206
	v_readlane_b32 s60, v252, 16
	v_lshl_or_b32 v188, s55, 8, v208
	v_ashrrev_i32_e32 v201, 31, v200
	v_readlane_b32 s74, v252, 30
	v_readlane_b32 s75, v252, 31
	v_ashrrev_i32_e32 v189, 31, v188
	v_lshlrev_b64 v[112:113], 13, v[200:201]
	v_readlane_b32 s72, v252, 28
	v_readlane_b32 s73, v252, 29
	s_mov_b64 s[82:83], s[74:75]
	v_lshlrev_b64 v[144:145], 2, v[188:189]
	v_readlane_b32 s61, v252, 17
	v_readlane_b32 s62, v252, 18
	v_readlane_b32 s63, v252, 19
	v_readlane_b32 s64, v252, 20
	v_readlane_b32 s65, v252, 21
	v_readlane_b32 s66, v252, 22
	v_readlane_b32 s67, v252, 23
	v_readlane_b32 s68, v252, 24
	v_readlane_b32 s69, v252, 25
	v_readlane_b32 s70, v252, 26
	v_readlane_b32 s71, v252, 27
	v_lshl_add_u64 v[190:191], s[82:83], 0, v[112:113]
	s_mov_b64 s[80:81], s[72:73]
	v_lshl_add_u64 v[230:231], v[190:191], 0, v[144:145]
	v_readlane_b32 s60, v252, 32
	global_load_dwordx4 v[196:199], v[230:231], off
	global_load_dwordx4 v[216:219], v[230:231], off offset:64
	global_load_dwordx4 v[222:225], v[230:231], off offset:512
	v_readlane_b32 s74, v252, 46
	v_readlane_b32 s75, v252, 47
	v_or_b32_e32 v202, 16, v200
	v_or_b32_e32 v192, 32, v200
	v_lshl_add_u64 v[112:113], s[74:75], 0, v[144:145]
	global_load_dwordx4 v[128:131], v[112:113], off
	global_load_dwordx4 v[120:123], v[112:113], off offset:64
	global_load_dwordx4 v[116:119], v[112:113], off offset:512
	global_load_dwordx4 v[226:229], v[230:231], off offset:576
	v_ashrrev_i32_e32 v203, 31, v202
	v_ashrrev_i32_e32 v193, 31, v192
	v_lshlrev_b64 v[146:147], 13, v[202:203]
	v_lshlrev_b64 v[148:149], 13, v[192:193]
	v_lshl_add_u64 v[146:147], s[82:83], 0, v[146:147]
	global_load_dwordx4 v[112:115], v[112:113], off offset:576
	v_lshl_add_u64 v[148:149], s[82:83], 0, v[148:149]
	v_lshl_add_u64 v[204:205], v[146:147], 0, v[144:145]
	v_lshl_add_u64 v[194:195], v[148:149], 0, v[144:145]
	global_load_dwordx4 v[172:175], v[204:205], off
	global_load_dwordx4 v[168:171], v[204:205], off offset:64
	global_load_dwordx4 v[164:167], v[204:205], off offset:512
	global_load_dwordx4 v[160:163], v[204:205], off offset:576
	global_load_dwordx4 v[156:159], v[194:195], off
	global_load_dwordx4 v[152:155], v[194:195], off offset:64
	global_load_dwordx4 v[148:151], v[194:195], off offset:512
	global_load_dwordx4 v[144:147], v[194:195], off offset:576
	v_and_b32_e32 v214, 64, v212
	v_xor_b32_e32 v213, 16, v212
	v_add_u32_e32 v214, 64, v214
	v_xor_b32_e32 v215, 32, v212
	v_cmp_lt_i32_e32 vcc, v213, v214
	v_lshlrev_b64 v[232:233], 11, v[200:201]
	v_lshl_add_u64 v[232:233], v[232:233], 0, v[188:189]
	v_cndmask_b32_e32 v213, v212, v213, vcc
	v_cmp_lt_i32_e32 vcc, v215, v214
	v_lshlrev_b32_e32 v214, 2, v213
	v_lshlrev_b64 v[232:233], 1, v[232:233]
	v_add_u32_e32 v232, v232, v253
	v_cndmask_b32_e32 v215, v212, v215, vcc
	v_lshlrev_b32_e32 v213, 2, v215
	v_lshl_add_u64 v[234:235], s[14:15], 0, v[232:233]
	v_or_b32_e32 v236, 0, v232
	v_mov_b32_e32 v237, v233
	v_lshl_add_u64 v[236:237], s[14:15], 0, v[236:237]
	v_readlane_b32 s61, v252, 33
	v_readlane_b32 s62, v252, 34
	v_readlane_b32 s63, v252, 35
	v_readlane_b32 s64, v252, 36
	v_readlane_b32 s65, v252, 37
	v_readlane_b32 s66, v252, 38
	v_readlane_b32 s67, v252, 39
	v_readlane_b32 s68, v252, 40
	v_readlane_b32 s69, v252, 41
	v_readlane_b32 s70, v252, 42
	v_readlane_b32 s71, v252, 43
	v_readlane_b32 s72, v252, 44
	v_readlane_b32 s73, v252, 45
	s_waitcnt vmcnt(0)
	v_pk_add_f32 v[138:139], v[138:139], v[198:199]
	v_pk_add_f32 v[136:137], v[136:137], v[196:197]
	v_pk_add_f32 v[142:143], v[142:143], v[218:219]
	v_pk_add_f32 v[140:141], v[140:141], v[216:217]
	v_pk_add_f32 v[134:135], v[134:135], v[224:225]
	v_pk_add_f32 v[132:133], v[132:133], v[222:223]
	v_mul_f32_e32 v215, v137, v137
	v_mul_f32_e32 v221, v139, v139
	v_pk_mul_f32 v[196:197], v[130:131], v[138:139]
	v_pk_mul_f32 v[198:199], v[128:129], v[136:137]
	v_mul_f32_e32 v238, v141, v141
	v_mul_f32_e32 v239, v143, v143
	global_store_dwordx4 v[230:231], v[136:139], off
	v_pk_mul_f32 v[216:217], v[122:123], v[142:143]
	v_pk_mul_f32 v[218:219], v[120:121], v[140:141]
	v_mul_f32_e32 v240, v133, v133
	v_mul_f32_e32 v241, v135, v135
	v_fmac_f32_e32 v215, v136, v136
	v_fmac_f32_e32 v221, v138, v138
	v_cvt_pk_bf16_f32 v136, v198, v199
	v_cvt_pk_bf16_f32 v137, v196, v197
	v_fmac_f32_e32 v238, v140, v140
	v_fmac_f32_e32 v239, v142, v142
	v_cvt_pk_bf16_f32 v138, v218, v219
	v_cvt_pk_bf16_f32 v139, v216, v217
	v_fmac_f32_e32 v240, v132, v132
	v_fmac_f32_e32 v241, v134, v134
	v_add_f32_e32 v197, v215, v221
	v_mov_b32_e32 v242, v136
	v_mov_b32_e32 v243, v137
	global_store_dwordx4 v[230:231], v[140:143], off offset:64
	v_add_f32_e32 v136, v238, v239
	v_pk_mul_f32 v[224:225], v[116:117], v[132:133]
	v_mov_b32_e32 v244, v138
	v_mov_b32_e32 v245, v139
	s_nop 1
	v_permlane16_swap_b32_e32 v242, v244
	v_permlane16_swap_b32_e32 v243, v245
	global_store_dwordx4 v[236:237], v[242:245], off
	global_store_dwordx4 v[230:231], v[132:135], off offset:512
	v_pk_mul_f32 v[222:223], v[118:119], v[134:135]
	v_cvt_pk_bf16_f32 v196, v224, v225
	v_add_f32_e32 v132, v240, v241
	v_add_f32_e32 v133, v197, v136
	v_add_f32_e32 v134, v133, v132
	v_or_b32_e32 v132, 0x100, v232
	v_mov_b32_e32 v133, v233
	v_cvt_pk_bf16_f32 v197, v222, v223
	v_lshl_add_u64 v[132:133], s[14:15], 0, v[132:133]
	v_pk_add_f32 v[126:127], v[126:127], v[228:229]
	v_pk_add_f32 v[124:125], v[124:125], v[226:227]
	v_mov_b32_e32 v246, v196
	v_mov_b32_e32 v247, v197
	v_mul_f32_e32 v132, v125, v125
	v_mul_f32_e32 v133, v127, v127
	v_fmac_f32_e32 v132, v124, v124
	v_fmac_f32_e32 v133, v126, v126
	v_add_f32_e32 v132, v132, v133
	v_add_f32_e32 v133, v134, v132
	ds_bpermute_b32 v134, v214, v133
	global_store_dwordx4 v[230:231], v[124:127], off offset:576
	v_or_b32_e32 v232, 0x100, v232
	s_nop 0
	v_pk_mul_f32 v[124:125], v[112:113], v[124:125]
	v_pk_mul_f32 v[126:127], v[114:115], v[126:127]
	v_cvt_pk_bf16_f32 v132, v124, v125
	s_waitcnt lgkmcnt(0)
	v_add_f32_e32 v124, v133, v134
	ds_bpermute_b32 v125, v213, v124
	v_cvt_pk_bf16_f32 v133, v126, v127
	v_lshl_add_u64 v[126:127], s[14:15], 0, v[232:233]
	v_mov_b32_e32 v248, v132
	v_mov_b32_e32 v249, v133
	s_nop 1
	v_permlane16_swap_b32_e32 v246, v248
	v_permlane16_swap_b32_e32 v247, v249
	global_store_dwordx4 v[126:127], v[246:249], off
	s_and_saveexec_b64 s[28:29], s[2:3]
	s_cbranch_execz .LBB0_854
	v_lshl_add_u64 v[126:127], v[200:201], 2, s[16:17]
	s_waitcnt lgkmcnt(0)
	v_add_f32_e32 v124, v124, v125
	global_atomic_add_f32 v[126:127], v124, off
.LBB0_854:
	s_or_b64 exec, exec, s[28:29]
	v_or_b32_e32 v196, 48, v200
	v_ashrrev_i32_e32 v197, 31, v196
	v_readlane_b32 s60, v252, 16
	s_waitcnt lgkmcnt(0)
	v_lshlrev_b64 v[124:125], 13, v[196:197]
	v_readlane_b32 s74, v252, 30
	v_readlane_b32 s75, v252, 31
	v_pk_add_f32 v[110:111], v[110:111], v[174:175]
	v_pk_add_f32 v[108:109], v[108:109], v[172:173]
	v_lshl_add_u64 v[124:125], s[74:75], 0, v[124:125]
	v_lshl_add_u64 v[198:199], v[188:189], 2, v[124:125]
	global_load_dwordx4 v[140:143], v[198:199], off
	global_load_dwordx4 v[136:139], v[198:199], off offset:64
	global_load_dwordx4 v[132:135], v[198:199], off offset:512
	global_load_dwordx4 v[124:127], v[198:199], off offset:576
	v_lshlrev_b64 v[216:217], 11, v[202:203]
	v_mul_f32_e32 v172, v109, v109
	v_mul_f32_e32 v173, v111, v111
	v_lshl_add_u64 v[216:217], v[216:217], 0, v[188:189]
	global_store_dwordx4 v[204:205], v[108:111], off
	v_fmac_f32_e32 v172, v108, v108
	v_fmac_f32_e32 v173, v110, v110
	v_pk_mul_f32 v[110:111], v[130:131], v[110:111]
	v_pk_mul_f32 v[108:109], v[128:129], v[108:109]
	v_add_f32_e32 v174, v172, v173
	v_cvt_pk_bf16_f32 v108, v108, v109
	v_cvt_pk_bf16_f32 v109, v110, v111
	v_lshlrev_b64 v[110:111], 1, v[216:217]
	v_add_u32_e32 v110, v110, v253
	v_lshl_add_u64 v[172:173], s[14:15], 0, v[110:111]
	v_pk_add_f32 v[106:107], v[106:107], v[170:171]
	v_pk_add_f32 v[104:105], v[104:105], v[168:169]
	v_mov_b32_e32 v242, v108
	v_mov_b32_e32 v243, v109
	v_mul_f32_e32 v108, v105, v105
	v_mul_f32_e32 v109, v107, v107
	global_store_dwordx4 v[204:205], v[104:107], off offset:64
	v_fmac_f32_e32 v108, v104, v104
	v_fmac_f32_e32 v109, v106, v106
	v_pk_mul_f32 v[106:107], v[122:123], v[106:107]
	v_pk_mul_f32 v[104:105], v[120:121], v[104:105]
	v_pk_add_f32 v[102:103], v[102:103], v[166:167]
	v_cvt_pk_bf16_f32 v104, v104, v105
	v_cvt_pk_bf16_f32 v105, v106, v107
	v_or_b32_e32 v106, 0, v110
	v_mov_b32_e32 v107, v111
	v_lshl_add_u64 v[106:107], s[14:15], 0, v[106:107]
	v_pk_add_f32 v[100:101], v[100:101], v[164:165]
	v_mov_b32_e32 v244, v104
	v_mov_b32_e32 v245, v105
	s_nop 1
	v_permlane16_swap_b32_e32 v242, v244
	v_permlane16_swap_b32_e32 v243, v245
	global_store_dwordx4 v[106:107], v[242:245], off
	v_mul_f32_e32 v104, v101, v101
	v_mul_f32_e32 v105, v103, v103
	global_store_dwordx4 v[204:205], v[100:103], off offset:512
	v_fmac_f32_e32 v104, v100, v100
	v_fmac_f32_e32 v105, v102, v102
	v_pk_mul_f32 v[102:103], v[118:119], v[102:103]
	v_pk_mul_f32 v[100:101], v[116:117], v[100:101]
	v_pk_add_f32 v[98:99], v[98:99], v[162:163]
	v_cvt_pk_bf16_f32 v100, v100, v101
	v_cvt_pk_bf16_f32 v101, v102, v103
	v_or_b32_e32 v102, 0x100, v110
	v_mov_b32_e32 v103, v111
	v_lshl_add_u64 v[102:103], s[14:15], 0, v[102:103]
	v_pk_add_f32 v[96:97], v[96:97], v[160:161]
	v_add_f32_e32 v108, v108, v109
	v_mov_b32_e32 v246, v100
	v_mov_b32_e32 v247, v101
	v_mul_f32_e32 v100, v97, v97
	v_mul_f32_e32 v101, v99, v99
	v_add_f32_e32 v108, v174, v108
	v_add_f32_e32 v104, v104, v105
	v_fmac_f32_e32 v100, v96, v96
	v_fmac_f32_e32 v101, v98, v98
	v_add_f32_e32 v104, v108, v104
	v_add_f32_e32 v100, v100, v101
	v_add_f32_e32 v101, v104, v100
	ds_bpermute_b32 v102, v214, v101
	global_store_dwordx4 v[204:205], v[96:99], off offset:576
	v_or_b32_e32 v110, 0x100, v110
	v_readlane_b32 s61, v252, 17
	v_pk_mul_f32 v[96:97], v[112:113], v[96:97]
	v_pk_mul_f32 v[98:99], v[114:115], v[98:99]
	v_cvt_pk_bf16_f32 v100, v96, v97
	s_waitcnt lgkmcnt(0)
	v_add_f32_e32 v96, v101, v102
	ds_bpermute_b32 v97, v213, v96
	v_cvt_pk_bf16_f32 v101, v98, v99
	v_lshl_add_u64 v[98:99], s[14:15], 0, v[110:111]
	v_readlane_b32 s62, v252, 18
	v_readlane_b32 s63, v252, 19
	v_readlane_b32 s64, v252, 20
	v_readlane_b32 s65, v252, 21
	v_readlane_b32 s66, v252, 22
	v_readlane_b32 s67, v252, 23
	v_readlane_b32 s68, v252, 24
	v_readlane_b32 s69, v252, 25
	v_readlane_b32 s70, v252, 26
	v_readlane_b32 s71, v252, 27
	v_readlane_b32 s72, v252, 28
	v_readlane_b32 s73, v252, 29
	v_mov_b32_e32 v248, v100
	v_mov_b32_e32 v249, v101
	s_nop 1
	v_permlane16_swap_b32_e32 v246, v248
	v_permlane16_swap_b32_e32 v247, v249
	global_store_dwordx4 v[98:99], v[246:249], off
	s_and_saveexec_b64 s[28:29], s[2:3]
	s_cbranch_execz .LBB0_856
	v_lshl_add_u64 v[98:99], v[202:203], 2, s[16:17]
	s_waitcnt lgkmcnt(0)
	v_add_f32_e32 v96, v96, v97
	global_atomic_add_f32 v[98:99], v96, off
.LBB0_856:
	s_or_b64 exec, exec, s[28:29]
	v_add_u32_e32 v160, 0x80, v200
	v_ashrrev_i32_e32 v161, 31, v160
	v_readlane_b32 s60, v252, 16
	s_waitcnt lgkmcnt(0)
	v_lshlrev_b64 v[96:97], 13, v[160:161]
	v_readlane_b32 s74, v252, 30
	v_readlane_b32 s75, v252, 31
	v_pk_add_f32 v[94:95], v[94:95], v[158:159]
	v_pk_add_f32 v[92:93], v[92:93], v[156:157]
	v_lshl_add_u64 v[96:97], s[74:75], 0, v[96:97]
	v_lshl_add_u64 v[162:163], v[188:189], 2, v[96:97]
	global_load_dwordx4 v[108:111], v[162:163], off
	global_load_dwordx4 v[104:107], v[162:163], off offset:64
	global_load_dwordx4 v[100:103], v[162:163], off offset:512
	global_load_dwordx4 v[96:99], v[162:163], off offset:576
	v_lshlrev_b64 v[164:165], 11, v[192:193]
	v_mul_f32_e32 v156, v93, v93
	v_mul_f32_e32 v157, v95, v95
	v_lshl_add_u64 v[164:165], v[164:165], 0, v[188:189]
	global_store_dwordx4 v[194:195], v[92:95], off
	v_fmac_f32_e32 v156, v92, v92
	v_fmac_f32_e32 v157, v94, v94
	v_pk_mul_f32 v[94:95], v[130:131], v[94:95]
	v_pk_mul_f32 v[92:93], v[128:129], v[92:93]
	v_add_f32_e32 v158, v156, v157
	v_cvt_pk_bf16_f32 v92, v92, v93
	v_cvt_pk_bf16_f32 v93, v94, v95
	v_lshlrev_b64 v[94:95], 1, v[164:165]
	v_add_u32_e32 v94, v94, v253
	v_lshl_add_u64 v[156:157], s[14:15], 0, v[94:95]
	v_pk_add_f32 v[90:91], v[90:91], v[154:155]
	v_pk_add_f32 v[88:89], v[88:89], v[152:153]
	v_mov_b32_e32 v242, v92
	v_mov_b32_e32 v243, v93
	v_mul_f32_e32 v92, v89, v89
	v_mul_f32_e32 v93, v91, v91
	global_store_dwordx4 v[194:195], v[88:91], off offset:64
	v_fmac_f32_e32 v92, v88, v88
	v_fmac_f32_e32 v93, v90, v90
	v_pk_mul_f32 v[90:91], v[122:123], v[90:91]
	v_pk_mul_f32 v[88:89], v[120:121], v[88:89]
	v_pk_add_f32 v[86:87], v[86:87], v[150:151]
	v_cvt_pk_bf16_f32 v88, v88, v89
	v_cvt_pk_bf16_f32 v89, v90, v91
	v_or_b32_e32 v90, 0, v94
	v_mov_b32_e32 v91, v95
	v_lshl_add_u64 v[90:91], s[14:15], 0, v[90:91]
	v_pk_add_f32 v[84:85], v[84:85], v[148:149]
	v_mov_b32_e32 v244, v88
	v_mov_b32_e32 v245, v89
	s_nop 1
	v_permlane16_swap_b32_e32 v242, v244
	v_permlane16_swap_b32_e32 v243, v245
	global_store_dwordx4 v[90:91], v[242:245], off
	v_mul_f32_e32 v88, v85, v85
	v_mul_f32_e32 v89, v87, v87
	global_store_dwordx4 v[194:195], v[84:87], off offset:512
	v_fmac_f32_e32 v88, v84, v84
	v_fmac_f32_e32 v89, v86, v86
	v_pk_mul_f32 v[86:87], v[118:119], v[86:87]
	v_pk_mul_f32 v[84:85], v[116:117], v[84:85]
	v_pk_add_f32 v[82:83], v[82:83], v[146:147]
	v_cvt_pk_bf16_f32 v84, v84, v85
	v_cvt_pk_bf16_f32 v85, v86, v87
	v_or_b32_e32 v86, 0x100, v94
	v_mov_b32_e32 v87, v95
	v_lshl_add_u64 v[86:87], s[14:15], 0, v[86:87]
	v_pk_add_f32 v[80:81], v[80:81], v[144:145]
	v_add_f32_e32 v92, v92, v93
	v_mov_b32_e32 v246, v84
	v_mov_b32_e32 v247, v85
	v_mul_f32_e32 v84, v81, v81
	v_mul_f32_e32 v85, v83, v83
	v_add_f32_e32 v92, v158, v92
	v_add_f32_e32 v88, v88, v89
	v_fmac_f32_e32 v84, v80, v80
	v_fmac_f32_e32 v85, v82, v82
	v_add_f32_e32 v88, v92, v88
	v_add_f32_e32 v84, v84, v85
	v_add_f32_e32 v85, v88, v84
	ds_bpermute_b32 v86, v214, v85
	global_store_dwordx4 v[194:195], v[80:83], off offset:576
	v_or_b32_e32 v94, 0x100, v94
	v_readlane_b32 s61, v252, 17
	v_pk_mul_f32 v[80:81], v[112:113], v[80:81]
	v_pk_mul_f32 v[82:83], v[114:115], v[82:83]
	v_cvt_pk_bf16_f32 v84, v80, v81
	s_waitcnt lgkmcnt(0)
	v_add_f32_e32 v80, v85, v86
	ds_bpermute_b32 v81, v213, v80
	v_cvt_pk_bf16_f32 v85, v82, v83
	v_lshl_add_u64 v[82:83], s[14:15], 0, v[94:95]
	v_readlane_b32 s62, v252, 18
	v_readlane_b32 s63, v252, 19
	v_readlane_b32 s64, v252, 20
	v_readlane_b32 s65, v252, 21
	v_readlane_b32 s66, v252, 22
	v_readlane_b32 s67, v252, 23
	v_readlane_b32 s68, v252, 24
	v_readlane_b32 s69, v252, 25
	v_readlane_b32 s70, v252, 26
	v_readlane_b32 s71, v252, 27
	v_readlane_b32 s72, v252, 28
	v_readlane_b32 s73, v252, 29
	v_mov_b32_e32 v248, v84
	v_mov_b32_e32 v249, v85
	s_nop 1
	v_permlane16_swap_b32_e32 v246, v248
	v_permlane16_swap_b32_e32 v247, v249
	global_store_dwordx4 v[82:83], v[246:249], off
	s_and_saveexec_b64 s[28:29], s[2:3]
	s_cbranch_execz .LBB0_858
	v_lshl_add_u64 v[82:83], v[192:193], 2, s[16:17]
	s_waitcnt lgkmcnt(0)
	v_add_f32_e32 v80, v80, v81
	global_atomic_add_f32 v[82:83], v80, off
.LBB0_858:
	s_or_b64 exec, exec, s[28:29]
	s_waitcnt lgkmcnt(0)
	v_lshl_add_u64 v[80:81], v[188:189], 2, v[190:191]
	v_lshl_add_u64 v[144:145], v[80:81], 0, s[24:25]
	v_add_co_u32_e32 v80, vcc, 0x120000, v80
	s_waitcnt vmcnt(19)
	v_pk_add_f32 v[78:79], v[78:79], v[142:143]
	v_addc_co_u32_e32 v81, vcc, 0, v81, vcc
	global_load_dwordx4 v[88:91], v[144:145], off offset:64
	global_load_dwordx4 v[84:87], v[144:145], off offset:512
	global_load_dwordx4 v[92:95], v[80:81], off
	s_nop 0
	global_load_dwordx4 v[80:83], v[144:145], off offset:576
	v_pk_add_f32 v[76:77], v[76:77], v[140:141]
	v_lshlrev_b64 v[146:147], 11, v[196:197]
	v_mul_f32_e32 v140, v77, v77
	v_mul_f32_e32 v141, v79, v79
	v_lshl_add_u64 v[146:147], v[146:147], 0, v[188:189]
	global_store_dwordx4 v[198:199], v[76:79], off
	v_fmac_f32_e32 v140, v76, v76
	v_fmac_f32_e32 v141, v78, v78
	v_pk_mul_f32 v[78:79], v[130:131], v[78:79]
	v_pk_mul_f32 v[76:77], v[128:129], v[76:77]
	v_add_f32_e32 v142, v140, v141
	v_cvt_pk_bf16_f32 v76, v76, v77
	v_cvt_pk_bf16_f32 v77, v78, v79
	v_lshlrev_b64 v[78:79], 1, v[146:147]
	v_add_u32_e32 v78, v78, v253
	v_lshl_add_u64 v[140:141], s[14:15], 0, v[78:79]
	s_waitcnt vmcnt(23)
	v_pk_add_f32 v[74:75], v[74:75], v[138:139]
	v_pk_add_f32 v[72:73], v[72:73], v[136:137]
	v_mov_b32_e32 v242, v76
	v_mov_b32_e32 v243, v77
	v_mul_f32_e32 v76, v73, v73
	v_mul_f32_e32 v77, v75, v75
	global_store_dwordx4 v[198:199], v[72:75], off offset:64
	v_fmac_f32_e32 v76, v72, v72
	v_fmac_f32_e32 v77, v74, v74
	v_pk_mul_f32 v[74:75], v[122:123], v[74:75]
	v_pk_mul_f32 v[72:73], v[120:121], v[72:73]
	s_waitcnt vmcnt(23)
	v_pk_add_f32 v[70:71], v[70:71], v[134:135]
	v_cvt_pk_bf16_f32 v72, v72, v73
	v_cvt_pk_bf16_f32 v73, v74, v75
	v_or_b32_e32 v74, 0, v78
	v_mov_b32_e32 v75, v79
	v_lshl_add_u64 v[74:75], s[14:15], 0, v[74:75]
	v_pk_add_f32 v[68:69], v[68:69], v[132:133]
	v_mov_b32_e32 v244, v72
	v_mov_b32_e32 v245, v73
	s_nop 1
	v_permlane16_swap_b32_e32 v242, v244
	v_permlane16_swap_b32_e32 v243, v245
	global_store_dwordx4 v[74:75], v[242:245], off
	v_mul_f32_e32 v72, v69, v69
	v_mul_f32_e32 v73, v71, v71
	global_store_dwordx4 v[198:199], v[68:71], off offset:512
	v_fmac_f32_e32 v72, v68, v68
	v_fmac_f32_e32 v73, v70, v70
	v_pk_mul_f32 v[70:71], v[118:119], v[70:71]
	v_pk_mul_f32 v[68:69], v[116:117], v[68:69]
	s_waitcnt vmcnt(24)
	v_pk_add_f32 v[66:67], v[66:67], v[126:127]
	v_cvt_pk_bf16_f32 v68, v68, v69
	v_cvt_pk_bf16_f32 v69, v70, v71
	v_or_b32_e32 v70, 0x100, v78
	v_mov_b32_e32 v71, v79
	v_lshl_add_u64 v[70:71], s[14:15], 0, v[70:71]
	v_pk_add_f32 v[64:65], v[64:65], v[124:125]
	v_add_f32_e32 v76, v76, v77
	v_mov_b32_e32 v246, v68
	v_mov_b32_e32 v247, v69
	v_mul_f32_e32 v68, v65, v65
	v_mul_f32_e32 v69, v67, v67
	v_add_f32_e32 v76, v142, v76
	v_add_f32_e32 v72, v72, v73
	v_fmac_f32_e32 v68, v64, v64
	v_fmac_f32_e32 v69, v66, v66
	v_add_f32_e32 v72, v76, v72
	v_add_f32_e32 v68, v68, v69
	v_add_f32_e32 v69, v72, v68
	ds_bpermute_b32 v70, v214, v69
	global_store_dwordx4 v[198:199], v[64:67], off offset:576
	v_or_b32_e32 v78, 0x100, v78
	s_nop 0
	v_pk_mul_f32 v[64:65], v[112:113], v[64:65]
	v_pk_mul_f32 v[66:67], v[114:115], v[66:67]
	v_cvt_pk_bf16_f32 v68, v64, v65
	s_waitcnt lgkmcnt(0)
	v_add_f32_e32 v64, v69, v70
	ds_bpermute_b32 v65, v213, v64
	v_cvt_pk_bf16_f32 v69, v66, v67
	v_lshl_add_u64 v[66:67], s[14:15], 0, v[78:79]
	v_mov_b32_e32 v248, v68
	v_mov_b32_e32 v249, v69
	s_nop 1
	v_permlane16_swap_b32_e32 v246, v248
	v_permlane16_swap_b32_e32 v247, v249
	global_store_dwordx4 v[66:67], v[246:249], off
	s_and_saveexec_b64 s[28:29], s[2:3]
	s_cbranch_execz .LBB0_860
	v_lshl_add_u64 v[66:67], v[196:197], 2, s[16:17]
	s_waitcnt lgkmcnt(0)
	v_add_f32_e32 v64, v64, v65
	global_atomic_add_f32 v[66:67], v64, off
.LBB0_860:
	s_or_b64 exec, exec, s[28:29]
	v_or_b32_e32 v124, 32, v160
	v_ashrrev_i32_e32 v125, 31, v124
	v_readlane_b32 s60, v252, 16
	s_waitcnt lgkmcnt(0)
	v_lshlrev_b64 v[64:65], 13, v[124:125]
	v_readlane_b32 s74, v252, 30
	v_readlane_b32 s75, v252, 31
	s_waitcnt vmcnt(19)
	v_pk_add_f32 v[62:63], v[62:63], v[110:111]
	v_pk_add_f32 v[60:61], v[60:61], v[108:109]
	v_lshl_add_u64 v[64:65], s[74:75], 0, v[64:65]
	v_lshl_add_u64 v[126:127], v[188:189], 2, v[64:65]
	global_load_dwordx4 v[76:79], v[126:127], off
	global_load_dwordx4 v[72:75], v[126:127], off offset:64
	global_load_dwordx4 v[68:71], v[126:127], off offset:512
	global_load_dwordx4 v[64:67], v[126:127], off offset:576
	v_lshlrev_b64 v[132:133], 11, v[160:161]
	v_mul_f32_e32 v108, v61, v61
	v_mul_f32_e32 v109, v63, v63
	v_lshl_add_u64 v[132:133], v[132:133], 0, v[188:189]
	global_store_dwordx4 v[162:163], v[60:63], off
	v_fmac_f32_e32 v108, v60, v60
	v_fmac_f32_e32 v109, v62, v62
	v_pk_mul_f32 v[62:63], v[130:131], v[62:63]
	v_pk_mul_f32 v[60:61], v[128:129], v[60:61]
	v_add_f32_e32 v110, v108, v109
	v_cvt_pk_bf16_f32 v60, v60, v61
	v_cvt_pk_bf16_f32 v61, v62, v63
	v_lshlrev_b64 v[62:63], 1, v[132:133]
	v_add_u32_e32 v62, v62, v253
	v_lshl_add_u64 v[108:109], s[14:15], 0, v[62:63]
	s_waitcnt vmcnt(23)
	v_pk_add_f32 v[58:59], v[58:59], v[106:107]
	v_pk_add_f32 v[56:57], v[56:57], v[104:105]
	v_mov_b32_e32 v242, v60
	v_mov_b32_e32 v243, v61
	v_mul_f32_e32 v60, v57, v57
	v_mul_f32_e32 v61, v59, v59
	global_store_dwordx4 v[162:163], v[56:59], off offset:64
	v_fmac_f32_e32 v60, v56, v56
	v_fmac_f32_e32 v61, v58, v58
	v_pk_mul_f32 v[58:59], v[122:123], v[58:59]
	v_pk_mul_f32 v[56:57], v[120:121], v[56:57]
	s_waitcnt vmcnt(23)
	v_pk_add_f32 v[54:55], v[54:55], v[102:103]
	v_cvt_pk_bf16_f32 v56, v56, v57
	v_cvt_pk_bf16_f32 v57, v58, v59
	v_or_b32_e32 v58, 0, v62
	v_mov_b32_e32 v59, v63
	v_lshl_add_u64 v[58:59], s[14:15], 0, v[58:59]
	v_pk_add_f32 v[52:53], v[52:53], v[100:101]
	v_mov_b32_e32 v244, v56
	v_mov_b32_e32 v245, v57
	s_nop 1
	v_permlane16_swap_b32_e32 v242, v244
	v_permlane16_swap_b32_e32 v243, v245
	global_store_dwordx4 v[58:59], v[242:245], off
	v_mul_f32_e32 v56, v53, v53
	v_mul_f32_e32 v57, v55, v55
	global_store_dwordx4 v[162:163], v[52:55], off offset:512
	v_fmac_f32_e32 v56, v52, v52
	v_fmac_f32_e32 v57, v54, v54
	v_pk_mul_f32 v[54:55], v[118:119], v[54:55]
	v_pk_mul_f32 v[52:53], v[116:117], v[52:53]
	s_waitcnt vmcnt(24)
	v_pk_add_f32 v[50:51], v[50:51], v[98:99]
	v_cvt_pk_bf16_f32 v52, v52, v53
	v_cvt_pk_bf16_f32 v53, v54, v55
	v_or_b32_e32 v54, 0x100, v62
	v_mov_b32_e32 v55, v63
	v_lshl_add_u64 v[54:55], s[14:15], 0, v[54:55]
	v_pk_add_f32 v[48:49], v[48:49], v[96:97]
	v_add_f32_e32 v60, v60, v61
	v_mov_b32_e32 v246, v52
	v_mov_b32_e32 v247, v53
	v_mul_f32_e32 v52, v49, v49
	v_mul_f32_e32 v53, v51, v51
	v_add_f32_e32 v60, v110, v60
	v_add_f32_e32 v56, v56, v57
	v_fmac_f32_e32 v52, v48, v48
	v_fmac_f32_e32 v53, v50, v50
	v_add_f32_e32 v56, v60, v56
	v_add_f32_e32 v52, v52, v53
	v_add_f32_e32 v53, v56, v52
	ds_bpermute_b32 v54, v214, v53
	global_store_dwordx4 v[162:163], v[48:51], off offset:576
	v_or_b32_e32 v62, 0x100, v62
	v_readlane_b32 s61, v252, 17
	v_pk_mul_f32 v[48:49], v[112:113], v[48:49]
	v_pk_mul_f32 v[50:51], v[114:115], v[50:51]
	v_cvt_pk_bf16_f32 v52, v48, v49
	s_waitcnt lgkmcnt(0)
	v_add_f32_e32 v48, v53, v54
	ds_bpermute_b32 v49, v213, v48
	v_cvt_pk_bf16_f32 v53, v50, v51
	v_lshl_add_u64 v[50:51], s[14:15], 0, v[62:63]
	v_readlane_b32 s62, v252, 18
	v_readlane_b32 s63, v252, 19
	v_readlane_b32 s64, v252, 20
	v_readlane_b32 s65, v252, 21
	v_readlane_b32 s66, v252, 22
	v_readlane_b32 s67, v252, 23
	v_readlane_b32 s68, v252, 24
	v_readlane_b32 s69, v252, 25
	v_readlane_b32 s70, v252, 26
	v_readlane_b32 s71, v252, 27
	v_readlane_b32 s72, v252, 28
	v_readlane_b32 s73, v252, 29
	v_mov_b32_e32 v248, v52
	v_mov_b32_e32 v249, v53
	s_nop 1
	v_permlane16_swap_b32_e32 v246, v248
	v_permlane16_swap_b32_e32 v247, v249
	global_store_dwordx4 v[50:51], v[246:249], off
	s_and_saveexec_b64 s[28:29], s[2:3]
	s_cbranch_execz .LBB0_862
	v_lshl_add_u64 v[50:51], v[160:161], 2, s[16:17]
	s_waitcnt lgkmcnt(0)
	v_add_f32_e32 v48, v48, v49
	global_atomic_add_f32 v[50:51], v48, off
.LBB0_862:
	s_or_b64 exec, exec, s[28:29]
	v_or_b32_e32 v96, 48, v160
	v_ashrrev_i32_e32 v97, 31, v96
	v_readlane_b32 s60, v252, 16
	s_waitcnt lgkmcnt(0)
	v_lshlrev_b64 v[48:49], 13, v[96:97]
	v_readlane_b32 s74, v252, 30
	v_readlane_b32 s75, v252, 31
	v_or_b32_e32 v100, 16, v160
	v_ashrrev_i32_e32 v101, 31, v100
	v_lshl_add_u64 v[48:49], s[74:75], 0, v[48:49]
	v_lshl_add_u64 v[98:99], v[188:189], 2, v[48:49]
	global_load_dwordx4 v[60:63], v[98:99], off
	global_load_dwordx4 v[56:59], v[98:99], off offset:64
	global_load_dwordx4 v[52:55], v[98:99], off offset:512
	global_load_dwordx4 v[48:51], v[98:99], off offset:576
	s_waitcnt vmcnt(21)
	v_pk_add_f32 v[46:47], v[46:47], v[94:95]
	v_pk_add_f32 v[44:45], v[44:45], v[92:93]
	v_lshlrev_b64 v[102:103], 11, v[100:101]
	v_mul_f32_e32 v92, v45, v45
	v_mul_f32_e32 v93, v47, v47
	v_lshl_add_u64 v[102:103], v[102:103], 0, v[188:189]
	global_store_dwordx4 v[144:145], v[44:47], off
	v_fmac_f32_e32 v92, v44, v44
	v_fmac_f32_e32 v93, v46, v46
	v_pk_mul_f32 v[46:47], v[130:131], v[46:47]
	v_pk_mul_f32 v[44:45], v[128:129], v[44:45]
	v_add_f32_e32 v94, v92, v93
	v_cvt_pk_bf16_f32 v44, v44, v45
	v_cvt_pk_bf16_f32 v45, v46, v47
	v_lshlrev_b64 v[46:47], 1, v[102:103]
	v_add_u32_e32 v46, v46, v253
	v_lshl_add_u64 v[92:93], s[14:15], 0, v[46:47]
	v_pk_add_f32 v[42:43], v[42:43], v[90:91]
	v_pk_add_f32 v[40:41], v[40:41], v[88:89]
	v_mov_b32_e32 v242, v44
	v_mov_b32_e32 v243, v45
	v_mul_f32_e32 v44, v41, v41
	v_mul_f32_e32 v45, v43, v43
	global_store_dwordx4 v[144:145], v[40:43], off offset:64
	v_fmac_f32_e32 v44, v40, v40
	v_fmac_f32_e32 v45, v42, v42
	v_pk_mul_f32 v[42:43], v[122:123], v[42:43]
	v_pk_mul_f32 v[40:41], v[120:121], v[40:41]
	v_pk_add_f32 v[38:39], v[38:39], v[86:87]
	v_cvt_pk_bf16_f32 v40, v40, v41
	v_cvt_pk_bf16_f32 v41, v42, v43
	v_or_b32_e32 v42, 0, v46
	v_mov_b32_e32 v43, v47
	v_lshl_add_u64 v[42:43], s[14:15], 0, v[42:43]
	v_pk_add_f32 v[36:37], v[36:37], v[84:85]
	v_mov_b32_e32 v244, v40
	v_mov_b32_e32 v245, v41
	s_nop 1
	v_permlane16_swap_b32_e32 v242, v244
	v_permlane16_swap_b32_e32 v243, v245
	global_store_dwordx4 v[42:43], v[242:245], off
	v_mul_f32_e32 v40, v37, v37
	v_mul_f32_e32 v41, v39, v39
	global_store_dwordx4 v[144:145], v[36:39], off offset:512
	v_fmac_f32_e32 v40, v36, v36
	v_fmac_f32_e32 v41, v38, v38
	v_pk_mul_f32 v[38:39], v[118:119], v[38:39]
	v_pk_mul_f32 v[36:37], v[116:117], v[36:37]
	s_waitcnt vmcnt(24)
	v_pk_add_f32 v[34:35], v[34:35], v[82:83]
	v_cvt_pk_bf16_f32 v36, v36, v37
	v_cvt_pk_bf16_f32 v37, v38, v39
	v_or_b32_e32 v38, 0x100, v46
	v_mov_b32_e32 v39, v47
	v_lshl_add_u64 v[38:39], s[14:15], 0, v[38:39]
	v_pk_add_f32 v[32:33], v[32:33], v[80:81]
	v_add_f32_e32 v44, v44, v45
	v_mov_b32_e32 v246, v36
	v_mov_b32_e32 v247, v37
	v_mul_f32_e32 v36, v33, v33
	v_mul_f32_e32 v37, v35, v35
	v_add_f32_e32 v44, v94, v44
	v_add_f32_e32 v40, v40, v41
	v_fmac_f32_e32 v36, v32, v32
	v_fmac_f32_e32 v37, v34, v34
	v_add_f32_e32 v40, v44, v40
	v_add_f32_e32 v36, v36, v37
	v_add_f32_e32 v37, v40, v36
	ds_bpermute_b32 v38, v214, v37
	global_store_dwordx4 v[144:145], v[32:35], off offset:576
	v_or_b32_e32 v46, 0x100, v46
	v_readlane_b32 s61, v252, 17
	v_pk_mul_f32 v[32:33], v[112:113], v[32:33]
	v_pk_mul_f32 v[34:35], v[114:115], v[34:35]
	v_cvt_pk_bf16_f32 v36, v32, v33
	s_waitcnt lgkmcnt(0)
	v_add_f32_e32 v32, v37, v38
	ds_bpermute_b32 v33, v213, v32
	v_cvt_pk_bf16_f32 v37, v34, v35
	v_lshl_add_u64 v[34:35], s[14:15], 0, v[46:47]
	v_readlane_b32 s62, v252, 18
	v_readlane_b32 s63, v252, 19
	v_readlane_b32 s64, v252, 20
	v_readlane_b32 s65, v252, 21
	v_readlane_b32 s66, v252, 22
	v_readlane_b32 s67, v252, 23
	v_readlane_b32 s68, v252, 24
	v_readlane_b32 s69, v252, 25
	v_readlane_b32 s70, v252, 26
	v_readlane_b32 s71, v252, 27
	v_readlane_b32 s72, v252, 28
	v_readlane_b32 s73, v252, 29
	v_mov_b32_e32 v248, v36
	v_mov_b32_e32 v249, v37
	s_nop 1
	v_permlane16_swap_b32_e32 v246, v248
	v_permlane16_swap_b32_e32 v247, v249
	global_store_dwordx4 v[34:35], v[246:249], off
	s_and_saveexec_b64 s[28:29], s[2:3]
	s_cbranch_execz .LBB0_864
	v_lshl_add_u64 v[34:35], v[100:101], 2, s[16:17]
	s_waitcnt lgkmcnt(0)
	v_add_f32_e32 v32, v32, v33
	global_atomic_add_f32 v[34:35], v32, off
.LBB0_864:
	s_or_b64 exec, exec, s[28:29]
	s_waitcnt vmcnt(19)
	v_pk_add_f32 v[30:31], v[30:31], v[78:79]
	v_pk_add_f32 v[28:29], v[28:29], v[76:77]
	s_waitcnt lgkmcnt(0)
	v_lshlrev_b64 v[32:33], 11, v[124:125]
	v_mul_f32_e32 v34, v29, v29
	v_mul_f32_e32 v35, v31, v31
	v_lshl_add_u64 v[32:33], v[32:33], 0, v[188:189]
	global_store_dwordx4 v[126:127], v[28:31], off
	v_fmac_f32_e32 v34, v28, v28
	v_fmac_f32_e32 v35, v30, v30
	v_pk_mul_f32 v[30:31], v[130:131], v[30:31]
	v_pk_mul_f32 v[28:29], v[128:129], v[28:29]
	s_waitcnt vmcnt(19)
	v_pk_add_f32 v[26:27], v[26:27], v[74:75]
	v_cvt_pk_bf16_f32 v28, v28, v29
	v_cvt_pk_bf16_f32 v29, v30, v31
	v_lshlrev_b64 v[30:31], 1, v[32:33]
	v_add_u32_e32 v30, v30, v253
	v_lshl_add_u64 v[32:33], s[14:15], 0, v[30:31]
	v_pk_add_f32 v[24:25], v[24:25], v[72:73]
	v_mov_b32_e32 v242, v28
	v_mov_b32_e32 v243, v29
	v_mul_f32_e32 v28, v25, v25
	v_mul_f32_e32 v29, v27, v27
	global_store_dwordx4 v[126:127], v[24:27], off offset:64
	v_fmac_f32_e32 v28, v24, v24
	v_fmac_f32_e32 v29, v26, v26
	v_pk_mul_f32 v[26:27], v[122:123], v[26:27]
	v_pk_mul_f32 v[24:25], v[120:121], v[24:25]
	s_waitcnt vmcnt(19)
	v_pk_add_f32 v[22:23], v[22:23], v[70:71]
	v_cvt_pk_bf16_f32 v24, v24, v25
	v_cvt_pk_bf16_f32 v25, v26, v27
	v_or_b32_e32 v26, 0, v30
	v_mov_b32_e32 v27, v31
	v_lshl_add_u64 v[26:27], s[14:15], 0, v[26:27]
	v_pk_add_f32 v[20:21], v[20:21], v[68:69]
	v_mov_b32_e32 v244, v24
	v_mov_b32_e32 v245, v25
	s_nop 1
	v_permlane16_swap_b32_e32 v242, v244
	v_permlane16_swap_b32_e32 v243, v245
	global_store_dwordx4 v[26:27], v[242:245], off
	v_mul_f32_e32 v24, v21, v21
	v_mul_f32_e32 v25, v23, v23
	global_store_dwordx4 v[126:127], v[20:23], off offset:512
	v_fmac_f32_e32 v24, v20, v20
	v_fmac_f32_e32 v25, v22, v22
	v_pk_mul_f32 v[22:23], v[118:119], v[22:23]
	v_pk_mul_f32 v[20:21], v[116:117], v[20:21]
	s_waitcnt vmcnt(20)
	v_pk_add_f32 v[18:19], v[18:19], v[66:67]
	v_cvt_pk_bf16_f32 v20, v20, v21
	v_cvt_pk_bf16_f32 v21, v22, v23
	v_or_b32_e32 v22, 0x100, v30
	v_mov_b32_e32 v23, v31
	v_lshl_add_u64 v[22:23], s[14:15], 0, v[22:23]
	v_pk_add_f32 v[16:17], v[16:17], v[64:65]
	v_add_f32_e32 v34, v34, v35
	v_add_f32_e32 v28, v28, v29
	v_mov_b32_e32 v246, v20
	v_mov_b32_e32 v247, v21
	v_mul_f32_e32 v20, v17, v17
	v_mul_f32_e32 v21, v19, v19
	v_add_f32_e32 v28, v34, v28
	v_add_f32_e32 v24, v24, v25
	v_fmac_f32_e32 v20, v16, v16
	v_fmac_f32_e32 v21, v18, v18
	v_add_f32_e32 v24, v28, v24
	v_add_f32_e32 v20, v20, v21
	v_add_f32_e32 v21, v24, v20
	ds_bpermute_b32 v22, v214, v21
	global_store_dwordx4 v[126:127], v[16:19], off offset:576
	v_or_b32_e32 v30, 0x100, v30
	s_nop 0
	v_pk_mul_f32 v[16:17], v[112:113], v[16:17]
	v_pk_mul_f32 v[18:19], v[114:115], v[18:19]
	v_cvt_pk_bf16_f32 v20, v16, v17
	s_waitcnt lgkmcnt(0)
	v_add_f32_e32 v16, v21, v22
	ds_bpermute_b32 v17, v213, v16
	v_cvt_pk_bf16_f32 v21, v18, v19
	v_lshl_add_u64 v[18:19], s[14:15], 0, v[30:31]
	v_mov_b32_e32 v248, v20
	v_mov_b32_e32 v249, v21
	s_nop 1
	v_permlane16_swap_b32_e32 v246, v248
	v_permlane16_swap_b32_e32 v247, v249
	global_store_dwordx4 v[18:19], v[246:249], off
	s_and_saveexec_b64 s[28:29], s[2:3]
	s_cbranch_execz .LBB0_866
	v_lshl_add_u64 v[18:19], v[124:125], 2, s[16:17]
	s_waitcnt lgkmcnt(0)
	v_add_f32_e32 v16, v16, v17
	global_atomic_add_f32 v[18:19], v16, off
.LBB0_866:
	s_or_b64 exec, exec, s[28:29]
	s_waitcnt vmcnt(15)
	v_pk_add_f32 v[14:15], v[14:15], v[62:63]
	v_pk_add_f32 v[12:13], v[12:13], v[60:61]
	s_waitcnt lgkmcnt(0)
	v_lshlrev_b64 v[16:17], 11, v[96:97]
	v_mul_f32_e32 v18, v13, v13
	v_mul_f32_e32 v19, v15, v15
	v_lshl_add_u64 v[16:17], v[16:17], 0, v[188:189]
	global_store_dwordx4 v[98:99], v[12:15], off
	v_fmac_f32_e32 v18, v12, v12
	v_fmac_f32_e32 v19, v14, v14
	v_pk_mul_f32 v[14:15], v[130:131], v[14:15]
	v_pk_mul_f32 v[12:13], v[128:129], v[12:13]
	s_waitcnt vmcnt(15)
	v_pk_add_f32 v[10:11], v[10:11], v[58:59]
	v_cvt_pk_bf16_f32 v12, v12, v13
	v_cvt_pk_bf16_f32 v13, v14, v15
	v_lshlrev_b64 v[14:15], 1, v[16:17]
	v_add_u32_e32 v14, v14, v253
	v_lshl_add_u64 v[16:17], s[14:15], 0, v[14:15]
	v_pk_add_f32 v[8:9], v[8:9], v[56:57]
	v_mov_b32_e32 v242, v12
	v_mov_b32_e32 v243, v13
	v_mul_f32_e32 v12, v9, v9
	v_mul_f32_e32 v13, v11, v11
	global_store_dwordx4 v[98:99], v[8:11], off offset:64
	v_fmac_f32_e32 v12, v8, v8
	v_fmac_f32_e32 v13, v10, v10
	v_pk_mul_f32 v[10:11], v[122:123], v[10:11]
	v_pk_mul_f32 v[8:9], v[120:121], v[8:9]
	s_waitcnt vmcnt(15)
	v_pk_add_f32 v[6:7], v[6:7], v[54:55]
	v_cvt_pk_bf16_f32 v8, v8, v9
	v_cvt_pk_bf16_f32 v9, v10, v11
	v_or_b32_e32 v10, 0, v14
	v_mov_b32_e32 v11, v15
	v_lshl_add_u64 v[10:11], s[14:15], 0, v[10:11]
	v_pk_add_f32 v[4:5], v[4:5], v[52:53]
	v_mov_b32_e32 v244, v8
	v_mov_b32_e32 v245, v9
	s_nop 1
	v_permlane16_swap_b32_e32 v242, v244
	v_permlane16_swap_b32_e32 v243, v245
	global_store_dwordx4 v[10:11], v[242:245], off
	v_mul_f32_e32 v8, v5, v5
	v_mul_f32_e32 v9, v7, v7
	global_store_dwordx4 v[98:99], v[4:7], off offset:512
	v_fmac_f32_e32 v8, v4, v4
	v_fmac_f32_e32 v9, v6, v6
	v_pk_mul_f32 v[6:7], v[118:119], v[6:7]
	v_pk_mul_f32 v[4:5], v[116:117], v[4:5]
	s_waitcnt vmcnt(16)
	v_pk_add_f32 v[2:3], v[2:3], v[50:51]
	v_cvt_pk_bf16_f32 v4, v4, v5
	v_cvt_pk_bf16_f32 v5, v6, v7
	v_or_b32_e32 v6, 0x100, v14
	v_mov_b32_e32 v7, v15
	v_lshl_add_u64 v[6:7], s[14:15], 0, v[6:7]
	v_pk_add_f32 v[0:1], v[0:1], v[48:49]
	v_add_f32_e32 v18, v18, v19
	v_add_f32_e32 v12, v12, v13
	v_mov_b32_e32 v246, v4
	v_mov_b32_e32 v247, v5
	v_mul_f32_e32 v4, v1, v1
	v_mul_f32_e32 v5, v3, v3
	v_add_f32_e32 v12, v18, v12
	v_add_f32_e32 v8, v8, v9
	v_fmac_f32_e32 v4, v0, v0
	v_fmac_f32_e32 v5, v2, v2
	v_add_f32_e32 v8, v12, v8
	v_add_f32_e32 v4, v4, v5
	v_add_f32_e32 v5, v8, v4
	ds_bpermute_b32 v6, v214, v5
	global_store_dwordx4 v[98:99], v[0:3], off offset:576
	v_or_b32_e32 v14, 0x100, v14
	s_nop 0
	v_pk_mul_f32 v[0:1], v[112:113], v[0:1]
	v_pk_mul_f32 v[2:3], v[114:115], v[2:3]
	v_cvt_pk_bf16_f32 v4, v0, v1
	s_waitcnt lgkmcnt(0)
	v_add_f32_e32 v0, v5, v6
	ds_bpermute_b32 v1, v213, v0
	v_cvt_pk_bf16_f32 v5, v2, v3
	v_lshl_add_u64 v[2:3], s[14:15], 0, v[14:15]
	v_mov_b32_e32 v248, v4
	v_mov_b32_e32 v249, v5
	s_nop 1
	v_permlane16_swap_b32_e32 v246, v248
	v_permlane16_swap_b32_e32 v247, v249
	global_store_dwordx4 v[2:3], v[246:249], off
	s_and_saveexec_b64 s[28:29], s[2:3]
	s_cbranch_execz .LBB0_868
	v_lshl_add_u64 v[2:3], v[96:97], 2, s[16:17]
	s_waitcnt lgkmcnt(0)
	v_add_f32_e32 v0, v0, v1
	global_atomic_add_f32 v[2:3], v0, off

.LBB0_1060:
	v_bfe_u32 v253, v220, 4, 1
	v_mul_u32_u24_e32 v253, 24, v253
	v_readlane_b32 s60, v252, 16
	v_lshl_add_u32 v64, s54, 8, v218
	v_readlane_b32 s61, v252, 17
	v_readlane_b32 s62, v252, 18
	v_readlane_b32 s63, v252, 19
	v_readlane_b32 s72, v252, 28
	v_readlane_b32 s73, v252, 29
	v_lshl_or_b32 v144, s55, 8, v221
	v_ashrrev_i32_e32 v65, 31, v64
	v_readlane_b32 s74, v252, 30
	v_readlane_b32 s75, v252, 31
	s_mov_b64 s[60:61], s[72:73]
	v_ashrrev_i32_e32 v145, 31, v144
	s_waitcnt lgkmcnt(0)
	v_lshlrev_b64 v[0:1], 13, v[64:65]
	s_mov_b64 s[62:63], s[74:75]
	v_lshlrev_b64 v[16:17], 2, v[144:145]
	v_lshl_add_u64 v[210:211], s[62:63], 0, v[0:1]
	v_readlane_b32 s66, v252, 22
	v_readlane_b32 s67, v252, 23
	v_lshl_add_u64 v[228:229], v[210:211], 0, v[16:17]
	s_mov_b64 s[54:55], s[66:67]
	global_load_dwordx4 v[28:31], v[228:229], off
	global_load_dwordx4 v[40:43], v[228:229], off offset:64
	global_load_dwordx4 v[52:55], v[228:229], off offset:512
	v_lshl_add_u64 v[0:1], s[54:55], 0, v[16:17]
	global_load_dwordx4 v[12:15], v[0:1], off
	global_load_dwordx4 v[8:11], v[0:1], off offset:64
	global_load_dwordx4 v[4:7], v[0:1], off offset:512
	global_load_dwordx4 v[60:63], v[228:229], off offset:576
	v_or_b32_e32 v66, 16, v64
	v_or_b32_e32 v212, 32, v64
	v_ashrrev_i32_e32 v67, 31, v66
	v_ashrrev_i32_e32 v213, 31, v212
	v_lshlrev_b64 v[18:19], 13, v[66:67]
	v_lshlrev_b64 v[20:21], 13, v[212:213]
	v_lshl_add_u64 v[18:19], s[62:63], 0, v[18:19]
	global_load_dwordx4 v[0:3], v[0:1], off offset:576
	v_lshl_add_u64 v[20:21], s[62:63], 0, v[20:21]
	v_lshl_add_u64 v[216:217], v[18:19], 0, v[16:17]
	v_lshl_add_u64 v[214:215], v[20:21], 0, v[16:17]
	global_load_dwordx4 v[56:59], v[216:217], off
	global_load_dwordx4 v[48:51], v[216:217], off offset:64
	global_load_dwordx4 v[36:39], v[216:217], off offset:512
	global_load_dwordx4 v[24:27], v[216:217], off offset:576
	global_load_dwordx4 v[44:47], v[214:215], off
	global_load_dwordx4 v[32:35], v[214:215], off offset:64
	global_load_dwordx4 v[20:23], v[214:215], off offset:512
	global_load_dwordx4 v[16:19], v[214:215], off offset:576
	v_and_b32_e32 v227, 64, v225
	v_xor_b32_e32 v226, 16, v225
	v_add_u32_e32 v227, 64, v227
	v_xor_b32_e32 v230, 32, v225
	v_cmp_lt_i32_e32 vcc, v226, v227
	v_readlane_b32 s64, v252, 20
	v_readlane_b32 s65, v252, 21
	v_cndmask_b32_e32 v226, v225, v226, vcc
	v_cmp_lt_i32_e32 vcc, v230, v227
	v_lshlrev_b32_e32 v227, 2, v226
	v_readlane_b32 s68, v252, 24
	v_cndmask_b32_e32 v232, v225, v230, vcc
	v_lshlrev_b64 v[230:231], 11, v[64:65]
	v_lshl_add_u64 v[230:231], v[230:231], 0, v[144:145]
	v_lshlrev_b64 v[230:231], 1, v[230:231]
	v_add_u32_e32 v230, v230, v253
	v_lshlrev_b32_e32 v226, 2, v232
	v_lshl_add_u64 v[232:233], s[12:13], 0, v[230:231]
	v_or_b32_e32 v234, 0, v230
	v_mov_b32_e32 v235, v231
	v_lshl_add_u64 v[234:235], s[12:13], 0, v[234:235]
	v_readlane_b32 s69, v252, 25
	v_readlane_b32 s70, v252, 26
	v_readlane_b32 s71, v252, 27
	s_waitcnt vmcnt(0)
	v_pk_add_f32 v[30:31], v[198:199], v[30:31]
	v_pk_add_f32 v[28:29], v[200:201], v[28:29]
	v_pk_add_f32 v[42:43], v[202:203], v[42:43]
	v_pk_add_f32 v[40:41], v[204:205], v[40:41]
	v_pk_add_f32 v[54:55], v[208:209], v[54:55]
	v_pk_add_f32 v[52:53], v[206:207], v[52:53]
	v_mul_f32_e32 v236, v29, v29
	v_mul_f32_e32 v237, v31, v31
	v_pk_mul_f32 v[198:199], v[14:15], v[30:31]
	v_pk_mul_f32 v[200:201], v[12:13], v[28:29]
	v_mul_f32_e32 v238, v41, v41
	v_mul_f32_e32 v239, v43, v43
	global_store_dwordx4 v[228:229], v[28:31], off
	v_mul_f32_e32 v240, v53, v53
	v_mul_f32_e32 v241, v55, v55
	v_fmac_f32_e32 v236, v28, v28
	v_fmac_f32_e32 v237, v30, v30
	v_cvt_pk_bf16_f32 v28, v200, v201
	v_cvt_pk_bf16_f32 v29, v198, v199
	v_fmac_f32_e32 v238, v40, v40
	v_fmac_f32_e32 v239, v42, v42
	v_fmac_f32_e32 v240, v52, v52
	v_fmac_f32_e32 v241, v54, v54
	v_add_f32_e32 v199, v236, v237
	v_mov_b32_e32 v242, v28
	v_mov_b32_e32 v243, v29
	global_store_dwordx4 v[228:229], v[40:43], off offset:64
	v_add_f32_e32 v28, v238, v239
	v_add_f32_e32 v29, v240, v241
	v_add_f32_e32 v28, v199, v28
	v_pk_mul_f32 v[202:203], v[10:11], v[42:43]
	v_pk_mul_f32 v[204:205], v[8:9], v[40:41]
	v_pk_mul_f32 v[206:207], v[6:7], v[54:55]
	v_pk_mul_f32 v[208:209], v[4:5], v[52:53]
	v_add_f32_e32 v40, v28, v29
	v_or_b32_e32 v28, 0x100, v230
	v_mov_b32_e32 v29, v231
	v_cvt_pk_bf16_f32 v30, v204, v205
	v_cvt_pk_bf16_f32 v31, v202, v203
	v_cvt_pk_bf16_f32 v198, v208, v209
	v_cvt_pk_bf16_f32 v199, v206, v207
	v_lshl_add_u64 v[28:29], s[12:13], 0, v[28:29]
	v_mov_b32_e32 v244, v30
	v_mov_b32_e32 v245, v31
	s_nop 1
	v_permlane16_swap_b32_e32 v242, v244
	v_permlane16_swap_b32_e32 v243, v245
	global_store_dwordx4 v[234:235], v[242:245], off
	global_store_dwordx4 v[228:229], v[52:55], off offset:512
	v_mov_b32_e32 v246, v198
	v_mov_b32_e32 v247, v199
	v_pk_add_f32 v[30:31], v[196:197], v[62:63]
	v_pk_add_f32 v[28:29], v[194:195], v[60:61]
	v_mul_f32_e32 v42, v31, v31
	v_mul_f32_e32 v41, v29, v29
	v_fmac_f32_e32 v41, v28, v28
	v_fmac_f32_e32 v42, v30, v30
	v_add_f32_e32 v41, v41, v42
	v_add_f32_e32 v41, v40, v41
	ds_bpermute_b32 v42, v227, v41
	global_store_dwordx4 v[228:229], v[28:31], off offset:576
	v_or_b32_e32 v230, 0x100, v230
	s_nop 0
	v_pk_mul_f32 v[28:29], v[0:1], v[28:29]
	v_pk_mul_f32 v[30:31], v[2:3], v[30:31]
	v_cvt_pk_bf16_f32 v40, v28, v29
	s_waitcnt lgkmcnt(0)
	v_add_f32_e32 v28, v41, v42
	ds_bpermute_b32 v29, v226, v28
	v_cvt_pk_bf16_f32 v41, v30, v31
	v_lshl_add_u64 v[30:31], s[12:13], 0, v[230:231]
	v_mov_b32_e32 v248, v40
	v_mov_b32_e32 v249, v41
	s_nop 1
	v_permlane16_swap_b32_e32 v246, v248
	v_permlane16_swap_b32_e32 v247, v249
	global_store_dwordx4 v[30:31], v[246:249], off
	s_and_saveexec_b64 s[24:25], s[2:3]
	s_cbranch_execz .LBB0_1062
	v_lshl_add_u64 v[30:31], v[64:65], 2, s[14:15]
	s_waitcnt lgkmcnt(0)
	v_add_f32_e32 v28, v28, v29
	global_atomic_add_f32 v[30:31], v28, off
.LBB0_1062:
	s_or_b64 exec, exec, s[24:25]
	v_or_b32_e32 v194, 48, v64
	v_ashrrev_i32_e32 v195, 31, v194
	v_readlane_b32 s60, v252, 16
	s_waitcnt lgkmcnt(0)
	v_lshlrev_b64 v[28:29], 13, v[194:195]
	v_readlane_b32 s74, v252, 30
	v_readlane_b32 s75, v252, 31
	v_pk_add_f32 v[58:59], v[192:193], v[58:59]
	v_pk_add_f32 v[56:57], v[190:191], v[56:57]
	v_lshl_add_u64 v[28:29], s[74:75], 0, v[28:29]
	v_lshl_add_u64 v[196:197], v[144:145], 2, v[28:29]
	global_load_dwordx4 v[60:63], v[196:197], off
	global_load_dwordx4 v[52:55], v[196:197], off offset:64
	global_load_dwordx4 v[40:43], v[196:197], off offset:512
	global_load_dwordx4 v[28:31], v[196:197], off offset:576
	v_lshlrev_b64 v[198:199], 11, v[66:67]
	v_mul_f32_e32 v65, v57, v57
	v_mul_f32_e32 v190, v59, v59
	v_lshl_add_u64 v[198:199], v[198:199], 0, v[144:145]
	global_store_dwordx4 v[216:217], v[56:59], off
	v_fmac_f32_e32 v65, v56, v56
	v_fmac_f32_e32 v190, v58, v58
	v_pk_mul_f32 v[58:59], v[14:15], v[58:59]
	v_pk_mul_f32 v[56:57], v[12:13], v[56:57]
	v_add_f32_e32 v65, v65, v190
	v_cvt_pk_bf16_f32 v56, v56, v57
	v_cvt_pk_bf16_f32 v57, v58, v59
	v_lshlrev_b64 v[58:59], 1, v[198:199]
	v_add_u32_e32 v58, v58, v253
	v_lshl_add_u64 v[190:191], s[12:13], 0, v[58:59]
	v_pk_add_f32 v[50:51], v[188:189], v[50:51]
	v_pk_add_f32 v[48:49], v[186:187], v[48:49]
	v_mov_b32_e32 v242, v56
	v_mov_b32_e32 v243, v57
	v_mul_f32_e32 v56, v49, v49
	v_mul_f32_e32 v57, v51, v51
	global_store_dwordx4 v[216:217], v[48:51], off offset:64
	v_fmac_f32_e32 v56, v48, v48
	v_fmac_f32_e32 v57, v50, v50
	v_pk_mul_f32 v[50:51], v[10:11], v[50:51]
	v_pk_mul_f32 v[48:49], v[8:9], v[48:49]
	v_pk_add_f32 v[38:39], v[184:185], v[38:39]
	v_cvt_pk_bf16_f32 v48, v48, v49
	v_cvt_pk_bf16_f32 v49, v50, v51
	v_or_b32_e32 v50, 0, v58
	v_mov_b32_e32 v51, v59
	v_lshl_add_u64 v[50:51], s[12:13], 0, v[50:51]
	v_pk_add_f32 v[36:37], v[182:183], v[36:37]
	v_mov_b32_e32 v244, v48
	v_mov_b32_e32 v245, v49
	s_nop 1
	v_permlane16_swap_b32_e32 v242, v244
	v_permlane16_swap_b32_e32 v243, v245
	global_store_dwordx4 v[50:51], v[242:245], off
	v_mul_f32_e32 v48, v37, v37
	v_mul_f32_e32 v49, v39, v39
	global_store_dwordx4 v[216:217], v[36:39], off offset:512
	v_fmac_f32_e32 v48, v36, v36
	v_fmac_f32_e32 v49, v38, v38
	v_pk_mul_f32 v[38:39], v[6:7], v[38:39]
	v_pk_mul_f32 v[36:37], v[4:5], v[36:37]
	v_pk_add_f32 v[26:27], v[180:181], v[26:27]
	v_cvt_pk_bf16_f32 v36, v36, v37
	v_cvt_pk_bf16_f32 v37, v38, v39
	v_or_b32_e32 v38, 0x100, v58
	v_mov_b32_e32 v39, v59
	v_lshl_add_u64 v[38:39], s[12:13], 0, v[38:39]
	v_pk_add_f32 v[24:25], v[178:179], v[24:25]
	v_add_f32_e32 v56, v56, v57
	v_mov_b32_e32 v246, v36
	v_mov_b32_e32 v247, v37
	v_mul_f32_e32 v36, v25, v25
	v_mul_f32_e32 v37, v27, v27
	v_add_f32_e32 v56, v65, v56
	v_add_f32_e32 v48, v48, v49
	v_fmac_f32_e32 v36, v24, v24
	v_fmac_f32_e32 v37, v26, v26
	v_add_f32_e32 v48, v56, v48
	v_add_f32_e32 v36, v36, v37
	v_add_f32_e32 v37, v48, v36
	ds_bpermute_b32 v38, v227, v37
	global_store_dwordx4 v[216:217], v[24:27], off offset:576
	v_or_b32_e32 v58, 0x100, v58
	v_readlane_b32 s61, v252, 17
	v_pk_mul_f32 v[24:25], v[0:1], v[24:25]
	v_pk_mul_f32 v[26:27], v[2:3], v[26:27]
	v_cvt_pk_bf16_f32 v36, v24, v25
	s_waitcnt lgkmcnt(0)
	v_add_f32_e32 v24, v37, v38
	ds_bpermute_b32 v25, v226, v24
	v_cvt_pk_bf16_f32 v37, v26, v27
	v_lshl_add_u64 v[26:27], s[12:13], 0, v[58:59]
	v_readlane_b32 s62, v252, 18
	v_readlane_b32 s63, v252, 19
	v_readlane_b32 s64, v252, 20
	v_readlane_b32 s65, v252, 21
	v_readlane_b32 s66, v252, 22
	v_readlane_b32 s67, v252, 23
	v_readlane_b32 s68, v252, 24
	v_readlane_b32 s69, v252, 25
	v_readlane_b32 s70, v252, 26
	v_readlane_b32 s71, v252, 27
	v_readlane_b32 s72, v252, 28
	v_readlane_b32 s73, v252, 29
	v_mov_b32_e32 v248, v36
	v_mov_b32_e32 v249, v37
	s_nop 1
	v_permlane16_swap_b32_e32 v246, v248
	v_permlane16_swap_b32_e32 v247, v249
	global_store_dwordx4 v[26:27], v[246:249], off
	s_and_saveexec_b64 s[24:25], s[2:3]
	s_cbranch_execz .LBB0_1064
	v_lshl_add_u64 v[26:27], v[66:67], 2, s[14:15]
	s_waitcnt lgkmcnt(0)
	v_add_f32_e32 v24, v24, v25
	global_atomic_add_f32 v[26:27], v24, off
.LBB0_1064:
	s_or_b64 exec, exec, s[24:25]
	v_add_u32_e32 v178, 0x80, v64
	v_ashrrev_i32_e32 v179, 31, v178
	v_readlane_b32 s60, v252, 16
	s_waitcnt lgkmcnt(0)
	v_lshlrev_b64 v[24:25], 13, v[178:179]
	v_readlane_b32 s74, v252, 30
	v_readlane_b32 s75, v252, 31
	v_pk_add_f32 v[46:47], v[176:177], v[46:47]
	v_pk_add_f32 v[44:45], v[174:175], v[44:45]
	v_lshl_add_u64 v[24:25], s[74:75], 0, v[24:25]
	v_lshl_add_u64 v[180:181], v[144:145], 2, v[24:25]
	global_load_dwordx4 v[64:67], v[180:181], off
	global_load_dwordx4 v[48:51], v[180:181], off offset:64
	global_load_dwordx4 v[36:39], v[180:181], off offset:512
	global_load_dwordx4 v[24:27], v[180:181], off offset:576
	v_lshlrev_b64 v[56:57], 11, v[212:213]
	v_mul_f32_e32 v58, v45, v45
	v_mul_f32_e32 v59, v47, v47
	v_lshl_add_u64 v[56:57], v[56:57], 0, v[144:145]
	global_store_dwordx4 v[214:215], v[44:47], off
	v_fmac_f32_e32 v58, v44, v44
	v_fmac_f32_e32 v59, v46, v46
	v_pk_mul_f32 v[46:47], v[14:15], v[46:47]
	v_pk_mul_f32 v[44:45], v[12:13], v[44:45]
	v_pk_add_f32 v[34:35], v[172:173], v[34:35]
	v_cvt_pk_bf16_f32 v44, v44, v45
	v_cvt_pk_bf16_f32 v45, v46, v47
	v_lshlrev_b64 v[46:47], 1, v[56:57]
	v_add_u32_e32 v46, v46, v253
	v_lshl_add_u64 v[56:57], s[12:13], 0, v[46:47]
	v_pk_add_f32 v[32:33], v[170:171], v[32:33]
	v_mov_b32_e32 v242, v44
	v_mov_b32_e32 v243, v45
	v_mul_f32_e32 v44, v33, v33
	v_mul_f32_e32 v45, v35, v35
	global_store_dwordx4 v[214:215], v[32:35], off offset:64
	v_fmac_f32_e32 v44, v32, v32
	v_fmac_f32_e32 v45, v34, v34
	v_pk_mul_f32 v[34:35], v[10:11], v[34:35]
	v_pk_mul_f32 v[32:33], v[8:9], v[32:33]
	v_pk_add_f32 v[22:23], v[168:169], v[22:23]
	v_cvt_pk_bf16_f32 v32, v32, v33
	v_cvt_pk_bf16_f32 v33, v34, v35
	v_or_b32_e32 v34, 0, v46
	v_mov_b32_e32 v35, v47
	v_lshl_add_u64 v[34:35], s[12:13], 0, v[34:35]
	v_pk_add_f32 v[20:21], v[166:167], v[20:21]
	v_mov_b32_e32 v244, v32
	v_mov_b32_e32 v245, v33
	s_nop 1
	v_permlane16_swap_b32_e32 v242, v244
	v_permlane16_swap_b32_e32 v243, v245
	global_store_dwordx4 v[34:35], v[242:245], off
	v_mul_f32_e32 v32, v21, v21
	v_mul_f32_e32 v33, v23, v23
	global_store_dwordx4 v[214:215], v[20:23], off offset:512
	v_fmac_f32_e32 v32, v20, v20
	v_fmac_f32_e32 v33, v22, v22
	v_pk_mul_f32 v[22:23], v[6:7], v[22:23]
	v_pk_mul_f32 v[20:21], v[4:5], v[20:21]
	v_pk_add_f32 v[18:19], v[164:165], v[18:19]
	v_cvt_pk_bf16_f32 v20, v20, v21
	v_cvt_pk_bf16_f32 v21, v22, v23
	v_or_b32_e32 v22, 0x100, v46
	v_mov_b32_e32 v23, v47
	v_lshl_add_u64 v[22:23], s[12:13], 0, v[22:23]
	v_pk_add_f32 v[16:17], v[162:163], v[16:17]
	v_add_f32_e32 v58, v58, v59
	v_add_f32_e32 v44, v44, v45
	v_mov_b32_e32 v246, v20
	v_mov_b32_e32 v247, v21
	v_mul_f32_e32 v20, v17, v17
	v_mul_f32_e32 v21, v19, v19
	v_add_f32_e32 v44, v58, v44
	v_add_f32_e32 v32, v32, v33
	v_fmac_f32_e32 v20, v16, v16
	v_fmac_f32_e32 v21, v18, v18
	v_add_f32_e32 v32, v44, v32
	v_add_f32_e32 v20, v20, v21
	v_add_f32_e32 v21, v32, v20
	ds_bpermute_b32 v22, v227, v21
	global_store_dwordx4 v[214:215], v[16:19], off offset:576
	v_or_b32_e32 v46, 0x100, v46
	v_readlane_b32 s61, v252, 17
	v_pk_mul_f32 v[16:17], v[0:1], v[16:17]
	v_pk_mul_f32 v[18:19], v[2:3], v[18:19]
	v_cvt_pk_bf16_f32 v20, v16, v17
	s_waitcnt lgkmcnt(0)
	v_add_f32_e32 v16, v21, v22
	ds_bpermute_b32 v17, v226, v16
	v_cvt_pk_bf16_f32 v21, v18, v19
	v_lshl_add_u64 v[18:19], s[12:13], 0, v[46:47]
	v_readlane_b32 s62, v252, 18
	v_readlane_b32 s63, v252, 19
	v_readlane_b32 s64, v252, 20
	v_readlane_b32 s65, v252, 21
	v_readlane_b32 s66, v252, 22
	v_readlane_b32 s67, v252, 23
	v_readlane_b32 s68, v252, 24
	v_readlane_b32 s69, v252, 25
	v_readlane_b32 s70, v252, 26
	v_readlane_b32 s71, v252, 27
	v_readlane_b32 s72, v252, 28
	v_readlane_b32 s73, v252, 29
	v_mov_b32_e32 v248, v20
	v_mov_b32_e32 v249, v21
	s_nop 1
	v_permlane16_swap_b32_e32 v246, v248
	v_permlane16_swap_b32_e32 v247, v249
	global_store_dwordx4 v[18:19], v[246:249], off
	s_and_saveexec_b64 s[24:25], s[2:3]
	s_cbranch_execz .LBB0_1066
	v_lshl_add_u64 v[18:19], v[212:213], 2, s[14:15]
	s_waitcnt lgkmcnt(0)
	v_add_f32_e32 v16, v16, v17
	global_atomic_add_f32 v[18:19], v16, off
.LBB0_1066:
	s_or_b64 exec, exec, s[24:25]
	s_waitcnt lgkmcnt(0)
	v_lshl_add_u64 v[16:17], v[144:145], 2, v[210:211]
	v_lshl_add_u64 v[162:163], v[16:17], 0, s[20:21]
	v_add_co_u32_e32 v16, vcc, 0x120000, v16
	v_lshlrev_b64 v[20:21], 11, v[194:195]
	s_nop 0
	v_addc_co_u32_e32 v17, vcc, 0, v17, vcc
	global_load_dwordx4 v[44:47], v[162:163], off offset:64
	global_load_dwordx4 v[32:35], v[162:163], off offset:512
	global_load_dwordx4 v[56:59], v[16:17], off
	s_nop 0
	global_load_dwordx4 v[16:19], v[162:163], off offset:576
	v_lshl_add_u64 v[164:165], v[20:21], 0, v[144:145]
	s_waitcnt vmcnt(23)
	v_pk_add_f32 v[22:23], v[160:161], v[62:63]
	v_pk_add_f32 v[20:21], v[158:159], v[60:61]
	v_mul_f32_e32 v61, v23, v23
	v_mul_f32_e32 v60, v21, v21
	v_fmac_f32_e32 v60, v20, v20
	v_fmac_f32_e32 v61, v22, v22
	global_store_dwordx4 v[196:197], v[20:23], off
	v_add_f32_e32 v62, v60, v61
	v_lshlrev_b64 v[60:61], 1, v[164:165]
	v_add_u32_e32 v60, v60, v253
	v_pk_mul_f32 v[22:23], v[14:15], v[22:23]
	v_pk_mul_f32 v[20:21], v[12:13], v[20:21]
	s_nop 0
	v_cvt_pk_bf16_f32 v20, v20, v21
	v_cvt_pk_bf16_f32 v21, v22, v23
	v_lshl_add_u64 v[22:23], s[12:13], 0, v[60:61]
	v_mov_b32_e32 v242, v20
	v_mov_b32_e32 v243, v21
	s_waitcnt vmcnt(23)
	v_pk_add_f32 v[22:23], v[156:157], v[54:55]
	v_pk_add_f32 v[20:21], v[154:155], v[52:53]
	v_mul_f32_e32 v53, v23, v23
	v_mul_f32_e32 v52, v21, v21
	global_store_dwordx4 v[196:197], v[20:23], off offset:64
	v_fmac_f32_e32 v52, v20, v20
	v_fmac_f32_e32 v53, v22, v22
	v_pk_mul_f32 v[22:23], v[10:11], v[22:23]
	v_pk_mul_f32 v[20:21], v[8:9], v[20:21]
	v_add_f32_e32 v52, v52, v53
	v_cvt_pk_bf16_f32 v20, v20, v21
	v_cvt_pk_bf16_f32 v21, v22, v23
	v_or_b32_e32 v22, 0, v60
	v_mov_b32_e32 v23, v61
	v_lshl_add_u64 v[22:23], s[12:13], 0, v[22:23]
	v_mov_b32_e32 v244, v20
	v_mov_b32_e32 v245, v21
	s_nop 1
	v_permlane16_swap_b32_e32 v242, v244
	v_permlane16_swap_b32_e32 v243, v245
	global_store_dwordx4 v[22:23], v[242:245], off
	s_waitcnt vmcnt(24)
	v_pk_add_f32 v[22:23], v[152:153], v[42:43]
	v_pk_add_f32 v[20:21], v[150:151], v[40:41]
	v_mul_f32_e32 v41, v23, v23
	v_mul_f32_e32 v40, v21, v21
	global_store_dwordx4 v[196:197], v[20:23], off offset:512
	v_fmac_f32_e32 v40, v20, v20
	v_fmac_f32_e32 v41, v22, v22
	v_pk_mul_f32 v[22:23], v[6:7], v[22:23]
	v_pk_mul_f32 v[20:21], v[4:5], v[20:21]
	v_add_f32_e32 v52, v62, v52
	v_cvt_pk_bf16_f32 v20, v20, v21
	v_cvt_pk_bf16_f32 v21, v22, v23
	v_or_b32_e32 v22, 0x100, v60
	v_mov_b32_e32 v23, v61
	v_lshl_add_u64 v[22:23], s[12:13], 0, v[22:23]
	v_mov_b32_e32 v246, v20
	v_mov_b32_e32 v247, v21
	s_waitcnt vmcnt(24)
	v_pk_add_f32 v[22:23], v[148:149], v[30:31]
	v_pk_add_f32 v[20:21], v[146:147], v[28:29]
	v_mul_f32_e32 v29, v23, v23
	v_mul_f32_e32 v28, v21, v21
	v_add_f32_e32 v40, v40, v41
	v_fmac_f32_e32 v28, v20, v20
	v_fmac_f32_e32 v29, v22, v22
	v_add_f32_e32 v40, v52, v40
	v_add_f32_e32 v28, v28, v29
	v_add_f32_e32 v29, v40, v28
	ds_bpermute_b32 v30, v227, v29
	global_store_dwordx4 v[196:197], v[20:23], off offset:576
	v_or_b32_e32 v60, 0x100, v60
	s_nop 0
	v_pk_mul_f32 v[20:21], v[0:1], v[20:21]
	v_pk_mul_f32 v[22:23], v[2:3], v[22:23]
	v_cvt_pk_bf16_f32 v28, v20, v21
	s_waitcnt lgkmcnt(0)
	v_add_f32_e32 v20, v29, v30
	ds_bpermute_b32 v21, v226, v20
	v_cvt_pk_bf16_f32 v29, v22, v23
	v_lshl_add_u64 v[22:23], s[12:13], 0, v[60:61]
	v_mov_b32_e32 v248, v28
	v_mov_b32_e32 v249, v29
	s_nop 1
	v_permlane16_swap_b32_e32 v246, v248
	v_permlane16_swap_b32_e32 v247, v249
	global_store_dwordx4 v[22:23], v[246:249], off
	s_and_saveexec_b64 s[24:25], s[2:3]
	s_cbranch_execz .LBB0_1068
	v_lshl_add_u64 v[22:23], v[194:195], 2, s[14:15]
	s_waitcnt lgkmcnt(0)
	v_add_f32_e32 v20, v20, v21
	global_atomic_add_f32 v[22:23], v20, off
.LBB0_1068:
	s_or_b64 exec, exec, s[24:25]
	v_or_b32_e32 v146, 32, v178
	v_ashrrev_i32_e32 v147, 31, v146
	v_readlane_b32 s60, v252, 16
	s_waitcnt lgkmcnt(0)
	v_lshlrev_b64 v[20:21], 13, v[146:147]
	v_readlane_b32 s74, v252, 30
	v_readlane_b32 s75, v252, 31
	v_lshlrev_b64 v[60:61], 11, v[178:179]
	v_lshl_add_u64 v[150:151], v[60:61], 0, v[144:145]
	v_lshl_add_u64 v[20:21], s[74:75], 0, v[20:21]
	v_lshl_add_u64 v[148:149], v[144:145], 2, v[20:21]
	global_load_dwordx4 v[52:55], v[148:149], off
	global_load_dwordx4 v[40:43], v[148:149], off offset:64
	global_load_dwordx4 v[28:31], v[148:149], off offset:512
	global_load_dwordx4 v[20:23], v[148:149], off offset:576
	s_waitcnt vmcnt(23)
	v_pk_add_f32 v[62:63], v[142:143], v[66:67]
	v_pk_add_f32 v[60:61], v[140:141], v[64:65]
	v_mul_f32_e32 v65, v63, v63
	v_mul_f32_e32 v64, v61, v61
	global_store_dwordx4 v[180:181], v[60:63], off
	v_fmac_f32_e32 v64, v60, v60
	v_fmac_f32_e32 v65, v62, v62
	v_pk_mul_f32 v[62:63], v[14:15], v[62:63]
	v_pk_mul_f32 v[60:61], v[12:13], v[60:61]
	v_add_f32_e32 v66, v64, v65
	v_cvt_pk_bf16_f32 v60, v60, v61
	v_cvt_pk_bf16_f32 v61, v62, v63
	v_lshlrev_b64 v[62:63], 1, v[150:151]
	v_add_u32_e32 v62, v62, v253
	v_lshl_add_u64 v[64:65], s[12:13], 0, v[62:63]
	s_waitcnt vmcnt(23)
	v_pk_add_f32 v[50:51], v[126:127], v[50:51]
	v_pk_add_f32 v[48:49], v[124:125], v[48:49]
	v_mov_b32_e32 v242, v60
	v_mov_b32_e32 v243, v61
	v_mul_f32_e32 v60, v49, v49
	v_mul_f32_e32 v61, v51, v51
	global_store_dwordx4 v[180:181], v[48:51], off offset:64
	v_fmac_f32_e32 v60, v48, v48
	v_fmac_f32_e32 v61, v50, v50
	v_pk_mul_f32 v[50:51], v[10:11], v[50:51]
	v_pk_mul_f32 v[48:49], v[8:9], v[48:49]
	s_waitcnt vmcnt(23)
	v_pk_add_f32 v[38:39], v[122:123], v[38:39]
	v_cvt_pk_bf16_f32 v48, v48, v49
	v_cvt_pk_bf16_f32 v49, v50, v51
	v_or_b32_e32 v50, 0, v62
	v_mov_b32_e32 v51, v63
	v_lshl_add_u64 v[50:51], s[12:13], 0, v[50:51]
	v_pk_add_f32 v[36:37], v[120:121], v[36:37]
	v_mov_b32_e32 v244, v48
	v_mov_b32_e32 v245, v49
	s_nop 1
	v_permlane16_swap_b32_e32 v242, v244
	v_permlane16_swap_b32_e32 v243, v245
	global_store_dwordx4 v[50:51], v[242:245], off
	v_mul_f32_e32 v48, v37, v37
	v_mul_f32_e32 v49, v39, v39
	global_store_dwordx4 v[180:181], v[36:39], off offset:512
	v_fmac_f32_e32 v48, v36, v36
	v_fmac_f32_e32 v49, v38, v38
	v_pk_mul_f32 v[38:39], v[6:7], v[38:39]
	v_pk_mul_f32 v[36:37], v[4:5], v[36:37]
	s_waitcnt vmcnt(24)
	v_pk_add_f32 v[26:27], v[118:119], v[26:27]
	v_cvt_pk_bf16_f32 v36, v36, v37
	v_cvt_pk_bf16_f32 v37, v38, v39
	v_or_b32_e32 v38, 0x100, v62
	v_mov_b32_e32 v39, v63
	v_lshl_add_u64 v[38:39], s[12:13], 0, v[38:39]
	v_pk_add_f32 v[24:25], v[116:117], v[24:25]
	v_add_f32_e32 v60, v60, v61
	v_mov_b32_e32 v246, v36
	v_mov_b32_e32 v247, v37
	v_mul_f32_e32 v36, v25, v25
	v_mul_f32_e32 v37, v27, v27
	v_add_f32_e32 v60, v66, v60
	v_add_f32_e32 v48, v48, v49
	v_fmac_f32_e32 v36, v24, v24
	v_fmac_f32_e32 v37, v26, v26
	v_add_f32_e32 v48, v60, v48
	v_add_f32_e32 v36, v36, v37
	v_add_f32_e32 v37, v48, v36
	ds_bpermute_b32 v38, v227, v37
	global_store_dwordx4 v[180:181], v[24:27], off offset:576
	v_or_b32_e32 v62, 0x100, v62
	v_readlane_b32 s61, v252, 17
	v_pk_mul_f32 v[24:25], v[0:1], v[24:25]
	v_pk_mul_f32 v[26:27], v[2:3], v[26:27]
	v_cvt_pk_bf16_f32 v36, v24, v25
	s_waitcnt lgkmcnt(0)
	v_add_f32_e32 v24, v37, v38
	ds_bpermute_b32 v25, v226, v24
	v_cvt_pk_bf16_f32 v37, v26, v27
	v_lshl_add_u64 v[26:27], s[12:13], 0, v[62:63]
	v_readlane_b32 s62, v252, 18
	v_readlane_b32 s63, v252, 19
	v_readlane_b32 s64, v252, 20
	v_readlane_b32 s65, v252, 21
	v_readlane_b32 s66, v252, 22
	v_readlane_b32 s67, v252, 23
	v_readlane_b32 s68, v252, 24
	v_readlane_b32 s69, v252, 25
	v_readlane_b32 s70, v252, 26
	v_readlane_b32 s71, v252, 27
	v_readlane_b32 s72, v252, 28
	v_readlane_b32 s73, v252, 29
	v_mov_b32_e32 v248, v36
	v_mov_b32_e32 v249, v37
	s_nop 1
	v_permlane16_swap_b32_e32 v246, v248
	v_permlane16_swap_b32_e32 v247, v249
	global_store_dwordx4 v[26:27], v[246:249], off
	s_and_saveexec_b64 s[24:25], s[2:3]
	s_cbranch_execz .LBB0_1070
	v_lshl_add_u64 v[26:27], v[178:179], 2, s[14:15]
	s_waitcnt lgkmcnt(0)
	v_add_f32_e32 v24, v24, v25
	global_atomic_add_f32 v[26:27], v24, off
.LBB0_1070:
	s_or_b64 exec, exec, s[24:25]
	v_or_b32_e32 v64, 48, v178
	v_ashrrev_i32_e32 v65, 31, v64
	v_readlane_b32 s60, v252, 16
	s_waitcnt lgkmcnt(0)
	v_lshlrev_b64 v[24:25], 13, v[64:65]
	v_readlane_b32 s74, v252, 30
	v_readlane_b32 s75, v252, 31
	v_or_b32_e32 v116, 16, v178
	v_ashrrev_i32_e32 v117, 31, v116
	v_lshl_add_u64 v[24:25], s[74:75], 0, v[24:25]
	v_lshl_add_u64 v[66:67], v[144:145], 2, v[24:25]
	global_load_dwordx4 v[60:63], v[66:67], off
	global_load_dwordx4 v[48:51], v[66:67], off offset:64
	global_load_dwordx4 v[36:39], v[66:67], off offset:512
	global_load_dwordx4 v[24:27], v[66:67], off offset:576
	s_waitcnt vmcnt(21)
	v_pk_add_f32 v[58:59], v[114:115], v[58:59]
	v_pk_add_f32 v[56:57], v[112:113], v[56:57]
	v_lshlrev_b64 v[118:119], 11, v[116:117]
	v_mul_f32_e32 v112, v57, v57
	v_mul_f32_e32 v113, v59, v59
	v_lshl_add_u64 v[118:119], v[118:119], 0, v[144:145]
	global_store_dwordx4 v[162:163], v[56:59], off
	v_fmac_f32_e32 v112, v56, v56
	v_fmac_f32_e32 v113, v58, v58
	v_pk_mul_f32 v[58:59], v[14:15], v[58:59]
	v_pk_mul_f32 v[56:57], v[12:13], v[56:57]
	v_add_f32_e32 v114, v112, v113
	v_cvt_pk_bf16_f32 v56, v56, v57
	v_cvt_pk_bf16_f32 v57, v58, v59
	v_lshlrev_b64 v[58:59], 1, v[118:119]
	v_add_u32_e32 v58, v58, v253
	v_lshl_add_u64 v[112:113], s[12:13], 0, v[58:59]
	v_pk_add_f32 v[46:47], v[110:111], v[46:47]
	v_pk_add_f32 v[44:45], v[108:109], v[44:45]
	v_mov_b32_e32 v242, v56
	v_mov_b32_e32 v243, v57
	v_mul_f32_e32 v56, v45, v45
	v_mul_f32_e32 v57, v47, v47
	global_store_dwordx4 v[162:163], v[44:47], off offset:64
	v_fmac_f32_e32 v56, v44, v44
	v_fmac_f32_e32 v57, v46, v46
	v_pk_mul_f32 v[46:47], v[10:11], v[46:47]
	v_pk_mul_f32 v[44:45], v[8:9], v[44:45]
	v_pk_add_f32 v[34:35], v[106:107], v[34:35]
	v_cvt_pk_bf16_f32 v44, v44, v45
	v_cvt_pk_bf16_f32 v45, v46, v47
	v_or_b32_e32 v46, 0, v58
	v_mov_b32_e32 v47, v59
	v_lshl_add_u64 v[46:47], s[12:13], 0, v[46:47]
	v_pk_add_f32 v[32:33], v[104:105], v[32:33]
	v_mov_b32_e32 v244, v44
	v_mov_b32_e32 v245, v45
	s_nop 1
	v_permlane16_swap_b32_e32 v242, v244
	v_permlane16_swap_b32_e32 v243, v245
	global_store_dwordx4 v[46:47], v[242:245], off
	v_mul_f32_e32 v44, v33, v33
	v_mul_f32_e32 v45, v35, v35
	global_store_dwordx4 v[162:163], v[32:35], off offset:512
	v_fmac_f32_e32 v44, v32, v32
	v_fmac_f32_e32 v45, v34, v34
	v_pk_mul_f32 v[34:35], v[6:7], v[34:35]
	v_pk_mul_f32 v[32:33], v[4:5], v[32:33]
	s_waitcnt vmcnt(24)
	v_pk_add_f32 v[18:19], v[102:103], v[18:19]
	v_cvt_pk_bf16_f32 v32, v32, v33
	v_cvt_pk_bf16_f32 v33, v34, v35
	v_or_b32_e32 v34, 0x100, v58
	v_mov_b32_e32 v35, v59
	v_lshl_add_u64 v[34:35], s[12:13], 0, v[34:35]
	v_pk_add_f32 v[16:17], v[100:101], v[16:17]
	v_add_f32_e32 v56, v56, v57
	v_mov_b32_e32 v246, v32
	v_mov_b32_e32 v247, v33
	v_mul_f32_e32 v32, v17, v17
	v_mul_f32_e32 v33, v19, v19
	v_add_f32_e32 v56, v114, v56
	v_add_f32_e32 v44, v44, v45
	v_fmac_f32_e32 v32, v16, v16
	v_fmac_f32_e32 v33, v18, v18
	v_add_f32_e32 v44, v56, v44
	v_add_f32_e32 v32, v32, v33
	v_add_f32_e32 v33, v44, v32
	ds_bpermute_b32 v34, v227, v33
	global_store_dwordx4 v[162:163], v[16:19], off offset:576
	v_or_b32_e32 v58, 0x100, v58
	v_readlane_b32 s61, v252, 17
	v_pk_mul_f32 v[16:17], v[0:1], v[16:17]
	v_pk_mul_f32 v[18:19], v[2:3], v[18:19]
	v_cvt_pk_bf16_f32 v32, v16, v17
	s_waitcnt lgkmcnt(0)
	v_add_f32_e32 v16, v33, v34
	ds_bpermute_b32 v17, v226, v16
	v_cvt_pk_bf16_f32 v33, v18, v19
	v_lshl_add_u64 v[18:19], s[12:13], 0, v[58:59]
	v_readlane_b32 s62, v252, 18
	v_readlane_b32 s63, v252, 19
	v_readlane_b32 s64, v252, 20
	v_readlane_b32 s65, v252, 21
	v_readlane_b32 s66, v252, 22
	v_readlane_b32 s67, v252, 23
	v_readlane_b32 s68, v252, 24
	v_readlane_b32 s69, v252, 25
	v_readlane_b32 s70, v252, 26
	v_readlane_b32 s71, v252, 27
	v_readlane_b32 s72, v252, 28
	v_readlane_b32 s73, v252, 29
	v_mov_b32_e32 v248, v32
	v_mov_b32_e32 v249, v33
	s_nop 1
	v_permlane16_swap_b32_e32 v246, v248
	v_permlane16_swap_b32_e32 v247, v249
	global_store_dwordx4 v[18:19], v[246:249], off
	s_and_saveexec_b64 s[24:25], s[2:3]
	s_cbranch_execz .LBB0_1072
	v_lshl_add_u64 v[18:19], v[116:117], 2, s[14:15]
	s_waitcnt lgkmcnt(0)
	v_add_f32_e32 v16, v16, v17
	global_atomic_add_f32 v[18:19], v16, off
.LBB0_1072:
	s_or_b64 exec, exec, s[24:25]
	s_waitcnt lgkmcnt(0)
	v_lshlrev_b64 v[16:17], 11, v[146:147]
	v_lshl_add_u64 v[32:33], v[16:17], 0, v[144:145]
	s_waitcnt vmcnt(19)
	v_pk_add_f32 v[18:19], v[98:99], v[54:55]
	v_pk_add_f32 v[16:17], v[96:97], v[52:53]
	v_mul_f32_e32 v35, v19, v19
	v_mul_f32_e32 v34, v17, v17
	global_store_dwordx4 v[148:149], v[16:19], off
	v_fmac_f32_e32 v34, v16, v16
	v_fmac_f32_e32 v35, v18, v18
	v_pk_mul_f32 v[18:19], v[14:15], v[18:19]
	v_pk_mul_f32 v[16:17], v[12:13], v[16:17]
	v_lshlrev_b64 v[32:33], 1, v[32:33]
	v_add_u32_e32 v32, v32, v253
	v_cvt_pk_bf16_f32 v16, v16, v17
	v_cvt_pk_bf16_f32 v17, v18, v19
	v_lshl_add_u64 v[18:19], s[12:13], 0, v[32:33]
	v_mov_b32_e32 v242, v16
	v_mov_b32_e32 v243, v17
	s_waitcnt vmcnt(19)
	v_pk_add_f32 v[18:19], v[94:95], v[42:43]
	v_pk_add_f32 v[16:17], v[92:93], v[40:41]
	v_add_f32_e32 v34, v34, v35
	v_mul_f32_e32 v35, v17, v17
	v_mul_f32_e32 v40, v19, v19
	global_store_dwordx4 v[148:149], v[16:19], off offset:64
	v_fmac_f32_e32 v35, v16, v16
	v_fmac_f32_e32 v40, v18, v18
	v_pk_mul_f32 v[18:19], v[10:11], v[18:19]
	v_pk_mul_f32 v[16:17], v[8:9], v[16:17]
	v_add_f32_e32 v35, v35, v40
	v_cvt_pk_bf16_f32 v16, v16, v17
	v_cvt_pk_bf16_f32 v17, v18, v19
	v_or_b32_e32 v18, 0, v32
	v_mov_b32_e32 v19, v33
	v_lshl_add_u64 v[18:19], s[12:13], 0, v[18:19]
	v_mov_b32_e32 v244, v16
	v_mov_b32_e32 v245, v17
	s_nop 1
	v_permlane16_swap_b32_e32 v242, v244
	v_permlane16_swap_b32_e32 v243, v245
	global_store_dwordx4 v[18:19], v[242:245], off
	s_waitcnt vmcnt(20)
	v_pk_add_f32 v[18:19], v[90:91], v[30:31]
	v_pk_add_f32 v[16:17], v[88:89], v[28:29]
	v_mul_f32_e32 v29, v19, v19
	v_mul_f32_e32 v28, v17, v17
	global_store_dwordx4 v[148:149], v[16:19], off offset:512
	v_fmac_f32_e32 v28, v16, v16
	v_fmac_f32_e32 v29, v18, v18
	v_pk_mul_f32 v[18:19], v[6:7], v[18:19]
	v_pk_mul_f32 v[16:17], v[4:5], v[16:17]
	v_add_f32_e32 v34, v34, v35
	v_cvt_pk_bf16_f32 v16, v16, v17
	v_cvt_pk_bf16_f32 v17, v18, v19
	v_or_b32_e32 v18, 0x100, v32
	v_mov_b32_e32 v19, v33
	v_lshl_add_u64 v[18:19], s[12:13], 0, v[18:19]
	v_mov_b32_e32 v246, v16
	v_mov_b32_e32 v247, v17
	s_waitcnt vmcnt(20)
	v_pk_add_f32 v[18:19], v[86:87], v[22:23]
	v_pk_add_f32 v[16:17], v[84:85], v[20:21]
	v_mul_f32_e32 v21, v19, v19
	v_mul_f32_e32 v20, v17, v17
	v_add_f32_e32 v28, v28, v29
	v_fmac_f32_e32 v20, v16, v16
	v_fmac_f32_e32 v21, v18, v18
	v_add_f32_e32 v28, v34, v28
	v_add_f32_e32 v20, v20, v21
	v_add_f32_e32 v21, v28, v20
	ds_bpermute_b32 v22, v227, v21
	global_store_dwordx4 v[148:149], v[16:19], off offset:576
	v_or_b32_e32 v32, 0x100, v32
	s_nop 0
	v_pk_mul_f32 v[16:17], v[0:1], v[16:17]
	v_pk_mul_f32 v[18:19], v[2:3], v[18:19]
	v_cvt_pk_bf16_f32 v20, v16, v17
	s_waitcnt lgkmcnt(0)
	v_add_f32_e32 v16, v21, v22
	ds_bpermute_b32 v17, v226, v16
	v_cvt_pk_bf16_f32 v21, v18, v19
	v_lshl_add_u64 v[18:19], s[12:13], 0, v[32:33]
	v_mov_b32_e32 v248, v20
	v_mov_b32_e32 v249, v21
	s_nop 1
	v_permlane16_swap_b32_e32 v246, v248
	v_permlane16_swap_b32_e32 v247, v249
	global_store_dwordx4 v[18:19], v[246:249], off
	s_and_saveexec_b64 s[24:25], s[2:3]
	s_cbranch_execz .LBB0_1074
	v_lshl_add_u64 v[18:19], v[146:147], 2, s[14:15]
	s_waitcnt lgkmcnt(0)
	v_add_f32_e32 v16, v16, v17
	global_atomic_add_f32 v[18:19], v16, off
.LBB0_1074:
	s_or_b64 exec, exec, s[24:25]
	s_waitcnt lgkmcnt(0)
	v_lshlrev_b64 v[16:17], 11, v[64:65]
	v_lshl_add_u64 v[20:21], v[16:17], 0, v[144:145]
	s_waitcnt vmcnt(15)
	v_pk_add_f32 v[16:17], v[80:81], v[60:61]
	v_pk_add_f32 v[18:19], v[82:83], v[62:63]
	v_mul_f32_e32 v22, v17, v17
	global_store_dwordx4 v[66:67], v[16:19], off
	v_fmac_f32_e32 v22, v16, v16
	v_pk_mul_f32 v[14:15], v[14:15], v[18:19]
	v_pk_mul_f32 v[12:13], v[12:13], v[16:17]
	v_lshlrev_b64 v[16:17], 1, v[20:21]
	v_add_u32_e32 v16, v16, v253
	v_cvt_pk_bf16_f32 v12, v12, v13
	v_cvt_pk_bf16_f32 v13, v14, v15
	v_lshl_add_u64 v[14:15], s[12:13], 0, v[16:17]
	v_mov_b32_e32 v242, v12
	v_mov_b32_e32 v243, v13
	s_waitcnt vmcnt(15)
	v_pk_add_f32 v[14:15], v[78:79], v[50:51]
	v_pk_add_f32 v[12:13], v[76:77], v[48:49]
	v_pk_mul_f32 v[10:11], v[10:11], v[14:15]
	v_pk_mul_f32 v[8:9], v[8:9], v[12:13]
	global_store_dwordx4 v[66:67], v[12:15], off offset:64
	v_cvt_pk_bf16_f32 v8, v8, v9
	v_cvt_pk_bf16_f32 v9, v10, v11
	v_or_b32_e32 v10, 0, v16
	v_mov_b32_e32 v11, v17
	v_lshl_add_u64 v[10:11], s[12:13], 0, v[10:11]
	v_mov_b32_e32 v244, v8
	v_mov_b32_e32 v245, v9
	s_nop 1
	v_permlane16_swap_b32_e32 v242, v244
	v_permlane16_swap_b32_e32 v243, v245
	global_store_dwordx4 v[10:11], v[242:245], off
	s_waitcnt vmcnt(16)
	v_pk_add_f32 v[10:11], v[74:75], v[38:39]
	v_pk_add_f32 v[8:9], v[72:73], v[36:37]
	v_pk_mul_f32 v[6:7], v[6:7], v[10:11]
	v_pk_mul_f32 v[4:5], v[4:5], v[8:9]
	v_mul_f32_e32 v23, v19, v19
	v_cvt_pk_bf16_f32 v4, v4, v5
	v_cvt_pk_bf16_f32 v5, v6, v7
	v_or_b32_e32 v6, 0x100, v16
	v_mov_b32_e32 v7, v17
	v_fmac_f32_e32 v23, v18, v18
	v_mul_f32_e32 v18, v13, v13
	v_mul_f32_e32 v19, v15, v15
	v_lshl_add_u64 v[6:7], s[12:13], 0, v[6:7]
	v_fmac_f32_e32 v18, v12, v12
	v_fmac_f32_e32 v19, v14, v14
	global_store_dwordx4 v[66:67], v[8:11], off offset:512
	v_mul_f32_e32 v12, v9, v9
	v_mul_f32_e32 v13, v11, v11
	v_mov_b32_e32 v246, v4
	v_mov_b32_e32 v247, v5
	s_waitcnt vmcnt(16)
	v_pk_add_f32 v[6:7], v[70:71], v[26:27]
	v_pk_add_f32 v[4:5], v[68:69], v[24:25]
	v_add_f32_e32 v22, v22, v23
	v_add_f32_e32 v18, v18, v19
	v_fmac_f32_e32 v12, v8, v8
	v_fmac_f32_e32 v13, v10, v10
	v_mul_f32_e32 v8, v5, v5
	v_mul_f32_e32 v9, v7, v7
	v_add_f32_e32 v18, v22, v18
	v_add_f32_e32 v12, v12, v13
	v_fmac_f32_e32 v8, v4, v4
	v_fmac_f32_e32 v9, v6, v6
	v_add_f32_e32 v12, v18, v12
	v_add_f32_e32 v8, v8, v9
	v_add_f32_e32 v8, v12, v8
	ds_bpermute_b32 v9, v227, v8
	v_pk_mul_f32 v[0:1], v[0:1], v[4:5]
	global_store_dwordx4 v[66:67], v[4:7], off offset:576
	v_pk_mul_f32 v[2:3], v[2:3], v[6:7]
	v_or_b32_e32 v16, 0x100, v16
	v_cvt_pk_bf16_f32 v4, v0, v1
	s_waitcnt lgkmcnt(0)
	v_add_f32_e32 v0, v8, v9
	ds_bpermute_b32 v1, v226, v0
	v_cvt_pk_bf16_f32 v5, v2, v3
	v_lshl_add_u64 v[2:3], s[12:13], 0, v[16:17]
	v_mov_b32_e32 v248, v4
	v_mov_b32_e32 v249, v5
	s_nop 1
	v_permlane16_swap_b32_e32 v246, v248
	v_permlane16_swap_b32_e32 v247, v249
	global_store_dwordx4 v[2:3], v[246:249], off
	s_and_saveexec_b64 s[24:25], s[2:3]
	s_cbranch_execz .LBB0_1076
	v_lshl_add_u64 v[2:3], v[64:65], 2, s[14:15]
	s_waitcnt lgkmcnt(0)
	v_add_f32_e32 v0, v0, v1
	global_atomic_add_f32 v[2:3], v0, off

	.amdhsa_kernel _Z8mega_fwd4Args
		.amdhsa_group_segment_fixed_size 0
		.amdhsa_private_segment_fixed_size 0
		.amdhsa_kernarg_size 464
		.amdhsa_user_sgpr_count 2
		.amdhsa_user_sgpr_dispatch_ptr 0
		.amdhsa_user_sgpr_queue_ptr 0
		.amdhsa_user_sgpr_kernarg_segment_ptr 1
		.amdhsa_user_sgpr_dispatch_id 0
		.amdhsa_user_sgpr_kernarg_preload_length 0
		.amdhsa_user_sgpr_kernarg_preload_offset 0
		.amdhsa_user_sgpr_private_segment_size 0
		.amdhsa_uses_dynamic_stack 0
		.amdhsa_enable_private_segment 0
		.amdhsa_system_sgpr_workgroup_id_x 1
		.amdhsa_system_sgpr_workgroup_id_y 0
		.amdhsa_system_sgpr_workgroup_id_z 0
		.amdhsa_system_sgpr_workgroup_info 0
		.amdhsa_system_vgpr_workitem_id 2
		.amdhsa_next_free_vgpr 254
		.amdhsa_next_free_sgpr 98
		.amdhsa_accum_offset 256
		.amdhsa_reserve_vcc 1
		.amdhsa_float_round_mode_32 0
		.amdhsa_float_round_mode_16_64 0
		.amdhsa_float_denorm_mode_32 3
		.amdhsa_float_denorm_mode_16_64 3
		.amdhsa_dx10_clamp 1
		.amdhsa_ieee_mode 1
		.amdhsa_fp16_overflow 0
		.amdhsa_tg_split 0
		.amdhsa_exception_fp_ieee_invalid_op 0
		.amdhsa_exception_fp_denorm_src 0
		.amdhsa_exception_fp_ieee_div_zero 0
		.amdhsa_exception_fp_ieee_overflow 0
		.amdhsa_exception_fp_ieee_underflow 0
		.amdhsa_exception_fp_ieee_inexact 0
		.amdhsa_exception_int_div_zero 0
	.end_amdhsa_kernel

amdhsa.kernels:
  - .agpr_count:     0
    .args:
      - .offset:         0
        .size:           208
        .value_kind:     by_value
      - .offset:         208
        .size:           4
        .value_kind:     hidden_block_count_x
      - .offset:         212
        .size:           4
        .value_kind:     hidden_block_count_y
      - .offset:         216
        .size:           4
        .value_kind:     hidden_block_count_z
      - .offset:         220
        .size:           2
        .value_kind:     hidden_group_size_x
      - .offset:         222
        .size:           2
        .value_kind:     hidden_group_size_y
      - .offset:         224
        .size:           2
        .value_kind:     hidden_group_size_z
      - .offset:         226
        .size:           2
        .value_kind:     hidden_remainder_x
      - .offset:         228
        .size:           2
        .value_kind:     hidden_remainder_y
      - .offset:         230
        .size:           2
        .value_kind:     hidden_remainder_z
      - .offset:         248
        .size:           8
        .value_kind:     hidden_global_offset_x
      - .offset:         256
        .size:           8
        .value_kind:     hidden_global_offset_y
      - .offset:         264
        .size:           8
        .value_kind:     hidden_global_offset_z
      - .offset:         272
        .size:           2
        .value_kind:     hidden_grid_dims
      - .offset:         296
        .size:           8
        .value_kind:     hidden_multigrid_sync_arg
      - .offset:         328
        .size:           4
        .value_kind:     hidden_dynamic_lds_size
    .group_segment_fixed_size: 0
    .kernarg_segment_align: 8
    .kernarg_segment_size: 464
    .language:       OpenCL C
    .language_version:
      - 2
      - 0
    .max_flat_workgroup_size: 512
    .name:           _Z8mega_fwd4Args
    .private_segment_fixed_size: 0
    .sgpr_count:     104
    .sgpr_spill_count: 164
    .symbol:         _Z8mega_fwd4Args.kd
    .uniform_work_group_size: 1
    .uses_dynamic_stack: false
    .vgpr_count:     254
    .vgpr_spill_count: 0
    .wavefront_size: 64
